# baseline (speedup 1.0000x reference)
; __device__ __forceinline__ void norm_phase(const Params& p, const float* hl, const float* hcs, int li, int which, int row0, int nrows, float* ccopy) {
;     ...
; #pragma unroll
;     for (int i = 0; i < 4; i++) {
;       v[i] = ((const float4*)src)[lane + i * 64];
;       if (ccopy && isc) ((float4*)(ccopy + (size_t)(row - TL) * D))[lane + i * 64] = v[i];
;       ss += v[i].x * v[i].x + v[i].y * v[i].y + v[i].z * v[i].z + v[i].w * v[i].w;
;     }
; #pragma unroll
;     for (int m = 32; m >= 1; m >>= 1) ss += __shfl_xor(ss, m);
;     float rstd = rsqrtf(ss * (1.f / D) + 1e-6f);
; #pragma unroll
;     for (int i = 0; i < 4; i++) {
;       int col = (lane + i * 64) * 4;
;       float4 g4 = *(const float4*)(g + col), sh = *(const float4*)(md + col), sc = *(const float4*)(md + D + col);
;       float y0 = v[i].x * rstd * g4.x * (1.f + sc.x) + sh.x;
;       float y1 = v[i].y * rstd * g4.y * (1.f + sc.y) + sh.y;
;       float y2 = v[i].z * rstd * g4.z * (1.f + sc.z) + sh.z;
;       float y3 = v[i].w * rstd * g4.w * (1.f + sc.w) + sh.w;
;       *(uint2*)(p.z + (size_t)row * D + col) = make_uint2(pack2(y0, y1), pack2(y2, y3));
;     }
.LBB0_115:
	s_or_b64 exec, exec, s[16:17]
	v_min_i32_e32 v18, 0x8000, v16
	v_ashrrev_i32_e32 v18, 12, v18
	v_mul_hi_i32_i24_e32 v37, 0x9000, v18
	v_mul_i32_i24_e32 v36, 0x9000, v18
	v_lshl_add_u64 v[36:37], s[76:77], 0, v[36:37]
	v_lshl_add_u64 v[56:57], v[36:37], 0, s[14:15]
	v_lshl_add_u64 v[48:49], v[56:57], 0, v[28:29]
	global_load_dwordx4 v[44:47], v[20:21], off
	v_lshl_add_u64 v[36:37], v[36:37], 0, v[28:29]
	global_load_dwordx4 v[48:51], v[48:49], off
	s_waitcnt vmcnt(5)
	v_pk_mul_f32 v[58:59], v[12:13], v[12:13]
	global_load_dwordx4 v[52:55], v[36:37], off
	v_lshl_add_u64 v[114:115], v[56:57], 0, v[30:31]
	v_lshl_add_u64 v[110:111], v[56:57], 0, v[32:33]
	v_lshl_add_u64 v[112:113], v[56:57], 0, v[34:35]
	global_load_dwordx4 v[74:77], v[20:21], off offset:1024
	global_load_dwordx4 v[78:81], v[114:115], off
	global_load_dwordx4 v[82:85], v[36:37], off offset:1024
	global_load_dwordx4 v[86:89], v[20:21], off offset:2048
	global_load_dwordx4 v[90:93], v[110:111], off
	global_load_dwordx4 v[94:97], v[36:37], off offset:2048
	global_load_dwordx4 v[98:101], v[20:21], off offset:3072
	global_load_dwordx4 v[102:105], v[112:113], off
	global_load_dwordx4 v[106:109], v[36:37], off offset:3072
	s_waitcnt vmcnt(14)
	v_pk_mul_f32 v[62:63], v[8:9], v[8:9]
	v_pk_mul_f32 v[60:61], v[14:15], v[14:15]
	v_pk_mul_f32 v[64:65], v[10:11], v[10:11]
	s_waitcnt vmcnt(13)
	v_pk_mul_f32 v[66:67], v[4:5], v[4:5]
	v_add_f32_e32 v18, v62, v63
	v_add_f32_e32 v58, v58, v59
	v_pk_mul_f32 v[68:69], v[6:7], v[6:7]
	s_waitcnt vmcnt(12)
	v_pk_mul_f32 v[70:71], v[0:1], v[0:1]
	v_add_f32_e32 v59, v66, v67
	v_add_f32_e32 v18, v18, v64
	v_add_f32_e32 v58, v58, v60
	v_pk_mul_f32 v[72:73], v[2:3], v[2:3]
	v_add_f32_e32 v62, v70, v71
	v_add_f32_e32 v59, v59, v68
	v_add_f32_e32 v18, v18, v65
	v_add_f32_e32 v58, v58, v61
	v_add_f32_e32 v60, v62, v72
	v_add_f32_e32 v59, v59, v69
	v_add_f32_e32 v18, v58, v18
	v_add_f32_e32 v60, v60, v73
	v_add_f32_e32 v18, v18, v59
	v_add_f32_e32 v18, v18, v60
	ds_bpermute_b32 v58, v38, v18
	v_add_u32_e32 v16, s4, v16
	v_lshl_add_u64 v[22:23], v[22:23], 0, s[10:11]
	s_waitcnt lgkmcnt(0)
	v_add_f32_e32 v18, v18, v58
	ds_bpermute_b32 v58, v39, v18
	s_waitcnt lgkmcnt(0)
	v_add_f32_e32 v18, v18, v58
	ds_bpermute_b32 v58, v40, v18
	s_waitcnt lgkmcnt(0)
	v_add_f32_e32 v18, v18, v58
	ds_bpermute_b32 v58, v41, v18
	s_waitcnt lgkmcnt(0)
	v_add_f32_e32 v18, v18, v58
	ds_bpermute_b32 v58, v42, v18
	s_waitcnt lgkmcnt(0)
	v_add_f32_e32 v18, v18, v58
	ds_bpermute_b32 v58, v43, v18
	s_waitcnt lgkmcnt(0)
	v_add_f32_e32 v18, v18, v58
	v_fmamk_f32 v18, v18, 0x3a800000, v17
	v_mul_f32_e32 v58, 0x4b800000, v18
	v_cmp_gt_f32_e32 vcc, s19, v18
	s_nop 1
	v_cndmask_b32_e32 v18, v18, v58, vcc
	v_rsq_f32_e32 v18, v18
	v_lshl_add_u64 v[58:59], v[56:57], 0, v[30:31]
	v_mul_f32_e32 v60, 0x45800000, v18
	v_cndmask_b32_e32 v18, v18, v60, vcc
	v_pk_mul_f32 v[12:13], v[12:13], v[18:19] op_sel_hi:[1,0]
	v_pk_mul_f32 v[14:15], v[14:15], v[18:19] op_sel_hi:[1,0]
	v_pk_mul_f32 v[8:9], v[8:9], v[18:19] op_sel_hi:[1,0]
	v_pk_mul_f32 v[10:11], v[10:11], v[18:19] op_sel_hi:[1,0]
	v_pk_mul_f32 v[4:5], v[4:5], v[18:19] op_sel_hi:[1,0]
	s_waitcnt vmcnt(0)
	v_pk_mul_f32 v[12:13], v[44:45], v[12:13]
	v_pk_mul_f32 v[14:15], v[46:47], v[14:15]
	v_pk_add_f32 v[44:45], v[48:49], 1.0 op_sel_hi:[1,0]
	v_pk_add_f32 v[46:47], v[50:51], 1.0 op_sel_hi:[1,0]
	v_pk_fma_f32 v[12:13], v[44:45], v[12:13], v[52:53]
	v_pk_fma_f32 v[14:15], v[14:15], v[46:47], v[54:55]
	v_cvt_pk_bf16_f32 v12, v12, v13
	v_cvt_pk_bf16_f32 v13, v14, v15
	global_store_dwordx2 v[24:25], v[12:13], off offset:-1024
	s_nop 0
	v_lshl_add_u64 v[52:53], v[56:57], 0, v[32:33]
	v_pk_mul_f32 v[6:7], v[6:7], v[18:19] op_sel_hi:[1,0]
	v_pk_mul_f32 v[0:1], v[0:1], v[18:19] op_sel_hi:[1,0]
	v_pk_mul_f32 v[2:3], v[2:3], v[18:19] op_sel_hi:[1,0]
	v_cmp_lt_i32_e32 vcc, s20, v16
	s_or_b64 s[6:7], vcc, s[6:7]
	v_pk_mul_f32 v[8:9], v[8:9], v[74:75]
	v_pk_add_f32 v[12:13], v[78:79], 1.0 op_sel_hi:[1,0]
	v_pk_mul_f32 v[10:11], v[10:11], v[76:77]
	v_pk_add_f32 v[14:15], v[80:81], 1.0 op_sel_hi:[1,0]
	v_pk_fma_f32 v[8:9], v[8:9], v[12:13], v[82:83]
	v_pk_fma_f32 v[10:11], v[10:11], v[14:15], v[84:85]
	v_cvt_pk_bf16_f32 v8, v8, v9
	v_cvt_pk_bf16_f32 v9, v10, v11
	global_store_dwordx2 v[24:25], v[8:9], off offset:-512
	s_nop 0
	v_lshl_add_u64 v[48:49], v[56:57], 0, v[34:35]
	v_pk_mul_f32 v[4:5], v[4:5], v[86:87]
	v_pk_add_f32 v[8:9], v[90:91], 1.0 op_sel_hi:[1,0]
	v_pk_mul_f32 v[6:7], v[6:7], v[88:89]
	v_pk_add_f32 v[10:11], v[92:93], 1.0 op_sel_hi:[1,0]
	v_pk_fma_f32 v[4:5], v[4:5], v[8:9], v[94:95]
	v_pk_fma_f32 v[6:7], v[6:7], v[10:11], v[96:97]
	v_cvt_pk_bf16_f32 v4, v4, v5
	v_cvt_pk_bf16_f32 v5, v6, v7
	global_store_dwordx2 v[24:25], v[4:5], off
	s_nop 0
	v_pk_mul_f32 v[0:1], v[0:1], v[98:99]
	v_pk_add_f32 v[4:5], v[102:103], 1.0 op_sel_hi:[1,0]
	v_pk_mul_f32 v[2:3], v[2:3], v[100:101]
	v_pk_add_f32 v[6:7], v[104:105], 1.0 op_sel_hi:[1,0]
	v_pk_fma_f32 v[0:1], v[0:1], v[4:5], v[106:107]
	v_pk_fma_f32 v[2:3], v[2:3], v[6:7], v[108:109]
	v_cvt_pk_bf16_f32 v0, v0, v1
	v_cvt_pk_bf16_f32 v1, v2, v3
	global_store_dwordx2 v[24:25], v[0:1], off offset:512
	v_lshl_add_u64 v[24:25], v[24:25], 0, s[12:13]
	s_andn2_b64 exec, exec, s[6:7]
	s_cbranch_execz .LBB0_128

; __device__ __forceinline__ float bf2f(bfr h) { return __uint_as_float(((unsigned)h) << 16); }
; template <int W>
; __device__ __forceinline__ void pool_tile(const Params& p, int row0, int g, int wave, int lane_in) {
;     ...
;   for (int ks = 0; ks < 4; ks++) {
; #pragma unroll
;     for (int m = 0; m < 2; m++) {
;       int tt = t0 + wave * 32 + m * 16 + fr;
;       int lo = max(tt - W / 2, 0), hi = min(tt + W - W / 2, S);
;       float sum[8];
; #pragma unroll
;       for (int e = 0; e < 8; e++) sum[e] = 0.f;
;       const bfr* colp = xp + (size_t)b * S * 512 + g * 128 + ks * 32 + fq * 8;
;       constexpr int WC = W < 8 ? W : 8;
;       bf16x8 xc = *(const bf16x8*)(colp + (size_t)tt * 512);
; #pragma unroll
;       for (int o0 = 0; o0 < W; o0 += WC) {
;         bf16x8 wv[WC];
; #pragma unroll
;         for (int o = 0; o < WC; o++) {
;           int rc = min(max(tt - W / 2 + o0 + o, 0), S - 1);
;           wv[o] = *(const bf16x8*)(colp + (size_t)rc * 512);
;         }
; #pragma unroll
;         for (int o = 0; o < WC; o++) {
;           int r = tt - W / 2 + o0 + o;
;           float wgt = (r >= 0 && r < S) ? 1.f : 0.f;
; #pragma unroll
;           for (int e = 0; e < 8; e++) sum[e] += wgt * bf2f((bfr)wv[o][e]);
;         }
;         __builtin_amdgcn_sched_barrier(0);
;       }
;       float invn = 1.f / (float)(hi - lo);
.LBB0_1155:
	v_lshl_add_u64 v[164:165], v[144:145], 0, s[36:37]
	v_lshl_add_u64 v[68:69], v[160:161], 0, s[36:37]
	global_load_dwordx4 v[64:67], v[164:165], off offset:768
	global_load_dwordx4 v[170:173], v[68:69], off
	v_lshl_add_u64 v[68:69], v[158:159], 0, s[36:37]
	global_load_dwordx4 v[174:177], v[68:69], off
	v_lshl_add_u64 v[68:69], v[156:157], 0, s[36:37]
	global_load_dwordx4 v[88:91], v[68:69], off
	v_lshl_add_u64 v[68:69], v[154:155], 0, s[36:37]
	global_load_dwordx4 v[84:87], v[68:69], off
	v_lshl_add_u64 v[68:69], v[152:153], 0, s[36:37]
	global_load_dwordx4 v[80:83], v[68:69], off
	v_lshl_add_u64 v[68:69], v[150:151], 0, s[36:37]
	global_load_dwordx4 v[76:79], v[68:69], off
	v_lshl_add_u64 v[68:69], v[148:149], 0, s[36:37]
	global_load_dwordx4 v[72:75], v[68:69], off
	v_lshl_add_u64 v[68:69], v[146:147], 0, s[36:37]
	global_load_dwordx4 v[68:71], v[68:69], off
	v_lshl_add_u64 v[166:167], v[162:163], 0, s[36:37]
	s_waitcnt vmcnt(7)
	v_and_b32_e32 v169, 0xffff0000, v170
	v_lshlrev_b32_e32 v168, 16, v170
	v_pk_fma_f32 v[168:169], v[94:95], v[168:169], 0 op_sel_hi:[1,1,0]
	s_waitcnt vmcnt(6)
	v_and_b32_e32 v179, 0xffff0000, v174
	v_lshlrev_b32_e32 v178, 16, v174
	v_pk_fma_f32 v[168:169], v[96:97], v[178:179], v[168:169]
	s_waitcnt vmcnt(5)
	v_and_b32_e32 v179, 0xffff0000, v88
	v_lshlrev_b32_e32 v178, 16, v88
	v_pk_fma_f32 v[168:169], v[98:99], v[178:179], v[168:169]
	s_waitcnt vmcnt(4)
	v_and_b32_e32 v179, 0xffff0000, v84
	v_lshlrev_b32_e32 v178, 16, v84
	v_pk_fma_f32 v[168:169], v[100:101], v[178:179], v[168:169]
	s_waitcnt vmcnt(3)
	v_and_b32_e32 v179, 0xffff0000, v80
	v_lshlrev_b32_e32 v178, 16, v80
	v_pk_fma_f32 v[168:169], v[102:103], v[178:179], v[168:169]
	s_waitcnt vmcnt(2)
	v_and_b32_e32 v179, 0xffff0000, v76
	v_lshlrev_b32_e32 v178, 16, v76
	v_pk_fma_f32 v[168:169], v[104:105], v[178:179], v[168:169]
	s_waitcnt vmcnt(1)
	v_and_b32_e32 v179, 0xffff0000, v72
	v_lshlrev_b32_e32 v178, 16, v72
	v_pk_fma_f32 v[168:169], v[106:107], v[178:179], v[168:169]
	v_and_b32_e32 v179, 0xffff0000, v171
	v_lshlrev_b32_e32 v178, 16, v171
	v_pk_fma_f32 v[170:171], v[94:95], v[178:179], 0 op_sel_hi:[1,1,0]
	v_and_b32_e32 v179, 0xffff0000, v175
	v_lshlrev_b32_e32 v178, 16, v175
	v_pk_fma_f32 v[170:171], v[96:97], v[178:179], v[170:171]
	v_and_b32_e32 v175, 0xffff0000, v89
	v_lshlrev_b32_e32 v174, 16, v89
	v_pk_fma_f32 v[88:89], v[98:99], v[174:175], v[170:171]
	v_and_b32_e32 v171, 0xffff0000, v85
	v_lshlrev_b32_e32 v170, 16, v85
	v_pk_fma_f32 v[84:85], v[100:101], v[170:171], v[88:89]
	v_and_b32_e32 v89, 0xffff0000, v81
	v_lshlrev_b32_e32 v88, 16, v81
	v_pk_fma_f32 v[80:81], v[102:103], v[88:89], v[84:85]
	v_and_b32_e32 v85, 0xffff0000, v77
	v_lshlrev_b32_e32 v84, 16, v77
	v_pk_fma_f32 v[76:77], v[104:105], v[84:85], v[80:81]
	v_and_b32_e32 v81, 0xffff0000, v73
	v_lshlrev_b32_e32 v80, 16, v73
	v_pk_fma_f32 v[72:73], v[106:107], v[80:81], v[76:77]
	v_and_b32_e32 v77, 0xffff0000, v172
	v_lshlrev_b32_e32 v76, 16, v172
	v_pk_fma_f32 v[76:77], v[94:95], v[76:77], 0 op_sel_hi:[1,1,0]
	v_and_b32_e32 v81, 0xffff0000, v176
	v_lshlrev_b32_e32 v80, 16, v176
	v_pk_fma_f32 v[76:77], v[96:97], v[80:81], v[76:77]
	v_and_b32_e32 v81, 0xffff0000, v90
	v_lshlrev_b32_e32 v80, 16, v90
	v_pk_fma_f32 v[76:77], v[98:99], v[80:81], v[76:77]
	v_and_b32_e32 v81, 0xffff0000, v86
	v_lshlrev_b32_e32 v80, 16, v86
	v_pk_fma_f32 v[76:77], v[100:101], v[80:81], v[76:77]
	v_and_b32_e32 v81, 0xffff0000, v82
	v_lshlrev_b32_e32 v80, 16, v82
	v_pk_fma_f32 v[76:77], v[102:103], v[80:81], v[76:77]
	v_and_b32_e32 v81, 0xffff0000, v78
	v_lshlrev_b32_e32 v80, 16, v78
	v_pk_fma_f32 v[76:77], v[104:105], v[80:81], v[76:77]
	v_and_b32_e32 v81, 0xffff0000, v74
	v_lshlrev_b32_e32 v80, 16, v74
	v_pk_fma_f32 v[76:77], v[106:107], v[80:81], v[76:77]
	v_and_b32_e32 v81, 0xffff0000, v173
	v_lshlrev_b32_e32 v80, 16, v173
	v_pk_fma_f32 v[80:81], v[94:95], v[80:81], 0 op_sel_hi:[1,1,0]
	v_and_b32_e32 v85, 0xffff0000, v177
	v_lshlrev_b32_e32 v84, 16, v177
	v_pk_fma_f32 v[80:81], v[96:97], v[84:85], v[80:81]
	v_and_b32_e32 v85, 0xffff0000, v91
	v_lshlrev_b32_e32 v84, 16, v91
	v_pk_fma_f32 v[80:81], v[98:99], v[84:85], v[80:81]
	v_and_b32_e32 v85, 0xffff0000, v87
	v_lshlrev_b32_e32 v84, 16, v87
	v_pk_fma_f32 v[80:81], v[100:101], v[84:85], v[80:81]
	v_and_b32_e32 v85, 0xffff0000, v83
	v_lshlrev_b32_e32 v84, 16, v83
	v_pk_fma_f32 v[80:81], v[102:103], v[84:85], v[80:81]
	v_and_b32_e32 v83, 0xffff0000, v79
	v_lshlrev_b32_e32 v82, 16, v79
	v_pk_fma_f32 v[78:79], v[104:105], v[82:83], v[80:81]
	v_and_b32_e32 v81, 0xffff0000, v75
	v_lshlrev_b32_e32 v80, 16, v75
	v_pk_fma_f32 v[74:75], v[106:107], v[80:81], v[78:79]
	s_waitcnt vmcnt(0)
	v_and_b32_e32 v91, 0xffff0000, v68
	v_lshlrev_b32_e32 v90, 16, v68
	v_and_b32_e32 v197, 0xffff0000, v69
	v_lshlrev_b32_e32 v196, 16, v69
	v_and_b32_e32 v199, 0xffff0000, v70
	v_lshlrev_b32_e32 v198, 16, v70
	v_and_b32_e32 v201, 0xffff0000, v71
	v_lshlrev_b32_e32 v200, 16, v71
	v_add_co_u32_e32 v192, vcc, s93, v164
	global_load_dwordx4 v[68:71], v[164:165], off offset:768
	global_load_dwordx4 v[78:81], v[164:165], off offset:1792
	global_load_dwordx4 v[82:85], v[164:165], off offset:2816
	global_load_dwordx4 v[86:89], v[164:165], off offset:3840
	v_addc_co_u32_e32 v193, vcc, 0, v165, vcc
	global_load_dwordx4 v[170:173], v[192:193], off offset:768
	global_load_dwordx4 v[174:177], v[192:193], off offset:1792
	global_load_dwordx4 v[178:181], v[192:193], off offset:2816
	s_nop 0
	global_load_dwordx4 v[192:195], v[192:193], off offset:3840
	s_waitcnt vmcnt(7)
; __device__ __forceinline__ float bf2f(bfr h) { return __uint_as_float(((unsigned)h) << 16); }
; template <int W>
; __device__ __forceinline__ void pool_tile(const Params& p, int row0, int g, int wave, int lane_in) {
;     ...
; #pragma unroll
;       for (int o0 = 0; o0 < W; o0 += WC) {
;         bf16x8 wv[WC];
; #pragma unroll
;         for (int o = 0; o < WC; o++) {
;           int rc = min(max(tt - W / 2 + o0 + o, 0), S - 1);
;           wv[o] = *(const bf16x8*)(colp + (size_t)rc * 512);
;         }
; #pragma unroll
;         for (int o = 0; o < WC; o++) {
;           int r = tt - W / 2 + o0 + o;
;           float wgt = (r >= 0 && r < S) ? 1.f : 0.f;
; #pragma unroll
;           for (int e = 0; e < 8; e++) sum[e] += wgt * bf2f((bfr)wv[o][e]);
;         }
;         __builtin_amdgcn_sched_barrier(0);
;       }
;       float invn = 1.f / (float)(hi - lo);
;       u32x4 pk;
; #pragma unroll
;       for (int e = 0; e < 4; e++)
;         pk[e] = pack2(sum[2 * e] * invn - bf2f((bfr)xc[2 * e]), sum[2 * e + 1] * invn - bf2f((bfr)xc[2 * e + 1]));
;       bf16x8 af = __builtin_bit_cast(bf16x8, pk);
; #pragma unroll
;       for (int n = 0; n < 8; n++) {
;         bf16x8 bfg = *(const bf16x8*)(wp + (size_t)(n * 16 + fr) * 128 + ks * 32 + fq * 8);
;         acc[m][n] = mfma16(af, bfg, acc[m][n]);
;       }
	v_and_b32_e32 v203, 0xffff0000, v68
	v_lshlrev_b32_e32 v202, 16, v68
	v_and_b32_e32 v205, 0xffff0000, v69
	v_lshlrev_b32_e32 v204, 16, v69
	v_and_b32_e32 v69, 0xffff0000, v70
	v_lshlrev_b32_e32 v68, 16, v70
	v_and_b32_e32 v207, 0xffff0000, v71
	v_lshlrev_b32_e32 v206, 16, v71
	v_pk_fma_f32 v[70:71], v[108:109], v[90:91], v[168:169]
	s_waitcnt vmcnt(6)
	v_and_b32_e32 v91, 0xffff0000, v78
	v_pk_add_f32 v[70:71], v[70:71], v[202:203]
	v_lshlrev_b32_e32 v90, 16, v78
	v_pk_add_f32 v[70:71], v[70:71], v[90:91]
	s_waitcnt vmcnt(5)
	v_and_b32_e32 v91, 0xffff0000, v82
	v_lshlrev_b32_e32 v90, 16, v82
	v_pk_add_f32 v[70:71], v[70:71], v[90:91]
	s_waitcnt vmcnt(4)
	v_and_b32_e32 v91, 0xffff0000, v86
	v_lshlrev_b32_e32 v90, 16, v86
	v_pk_add_f32 v[70:71], v[70:71], v[90:91]
	s_waitcnt vmcnt(3)
	v_and_b32_e32 v91, 0xffff0000, v170
	v_lshlrev_b32_e32 v90, 16, v170
	v_pk_add_f32 v[70:71], v[70:71], v[90:91]
	s_waitcnt vmcnt(2)
	v_and_b32_e32 v91, 0xffff0000, v174
	v_lshlrev_b32_e32 v90, 16, v174
	v_pk_add_f32 v[70:71], v[70:71], v[90:91]
	s_waitcnt vmcnt(1)
	v_and_b32_e32 v91, 0xffff0000, v178
	v_lshlrev_b32_e32 v90, 16, v178
	v_pk_add_f32 v[70:71], v[70:71], v[90:91]
	s_waitcnt vmcnt(0)
	v_and_b32_e32 v91, 0xffff0000, v192
	v_lshlrev_b32_e32 v90, 16, v192
	v_pk_add_f32 v[70:71], v[70:71], v[90:91]
	v_and_b32_e32 v91, 0xffff0000, v64
	v_lshlrev_b32_e32 v90, 16, v64
	v_pk_fma_f32 v[70:71], v[110:111], v[70:71], v[90:91] neg_lo:[0,0,1] neg_hi:[0,0,1]
	s_mov_b32 s5, 0x19000
	v_cvt_pk_bf16_f32 v64, v70, v71
	v_pk_fma_f32 v[70:71], v[108:109], v[196:197], v[72:73]
	v_and_b32_e32 v73, 0xffff0000, v79
	v_pk_add_f32 v[70:71], v[70:71], v[204:205]
	v_lshlrev_b32_e32 v72, 16, v79
	v_pk_add_f32 v[70:71], v[70:71], v[72:73]
	v_and_b32_e32 v73, 0xffff0000, v83
	v_lshlrev_b32_e32 v72, 16, v83
	v_pk_add_f32 v[70:71], v[70:71], v[72:73]
	v_and_b32_e32 v73, 0xffff0000, v87
	v_lshlrev_b32_e32 v72, 16, v87
	v_pk_add_f32 v[70:71], v[70:71], v[72:73]
	v_and_b32_e32 v73, 0xffff0000, v171
	v_lshlrev_b32_e32 v72, 16, v171
	v_pk_add_f32 v[70:71], v[70:71], v[72:73]
	v_and_b32_e32 v73, 0xffff0000, v175
	v_lshlrev_b32_e32 v72, 16, v175
	v_pk_add_f32 v[70:71], v[70:71], v[72:73]
	v_and_b32_e32 v73, 0xffff0000, v179
	v_lshlrev_b32_e32 v72, 16, v179
	v_pk_add_f32 v[70:71], v[70:71], v[72:73]
	v_and_b32_e32 v73, 0xffff0000, v193
	v_lshlrev_b32_e32 v72, 16, v193
	v_pk_add_f32 v[70:71], v[70:71], v[72:73]
	v_and_b32_e32 v73, 0xffff0000, v65
	v_lshlrev_b32_e32 v72, 16, v65
	v_pk_fma_f32 v[70:71], v[110:111], v[70:71], v[72:73] neg_lo:[0,0,1] neg_hi:[0,0,1]
	v_add_co_u32_e32 v168, vcc, s5, v166
	v_cvt_pk_bf16_f32 v65, v70, v71
	v_pk_fma_f32 v[70:71], v[108:109], v[198:199], v[76:77]
	v_addc_co_u32_e32 v169, vcc, 0, v167, vcc
	v_pk_add_f32 v[68:69], v[70:71], v[68:69]
	v_and_b32_e32 v71, 0xffff0000, v80
	v_lshlrev_b32_e32 v70, 16, v80
	v_pk_add_f32 v[68:69], v[68:69], v[70:71]
	v_and_b32_e32 v71, 0xffff0000, v84
	v_lshlrev_b32_e32 v70, 16, v84
	v_pk_add_f32 v[68:69], v[68:69], v[70:71]
	v_and_b32_e32 v71, 0xffff0000, v88
	v_lshlrev_b32_e32 v70, 16, v88
	v_pk_add_f32 v[68:69], v[68:69], v[70:71]
	v_and_b32_e32 v71, 0xffff0000, v172
	v_lshlrev_b32_e32 v70, 16, v172
	v_pk_add_f32 v[68:69], v[68:69], v[70:71]
	v_and_b32_e32 v71, 0xffff0000, v176
	v_lshlrev_b32_e32 v70, 16, v176
	v_pk_add_f32 v[68:69], v[68:69], v[70:71]
	v_and_b32_e32 v71, 0xffff0000, v180
	v_lshlrev_b32_e32 v70, 16, v180
	v_pk_add_f32 v[68:69], v[68:69], v[70:71]
	v_and_b32_e32 v71, 0xffff0000, v194
	v_lshlrev_b32_e32 v70, 16, v194
	v_pk_add_f32 v[68:69], v[68:69], v[70:71]
	v_and_b32_e32 v71, 0xffff0000, v66
	v_lshlrev_b32_e32 v70, 16, v66
	v_pk_fma_f32 v[68:69], v[110:111], v[68:69], v[70:71] neg_lo:[0,0,1] neg_hi:[0,0,1]
	v_and_b32_e32 v71, 0xffff0000, v81
	v_cvt_pk_bf16_f32 v66, v68, v69
	v_pk_fma_f32 v[68:69], v[108:109], v[200:201], v[74:75]
	v_lshlrev_b32_e32 v70, 16, v81
	v_pk_add_f32 v[68:69], v[68:69], v[206:207]
	s_mov_b32 s5, 0x1b000
	v_pk_add_f32 v[68:69], v[68:69], v[70:71]
	v_and_b32_e32 v71, 0xffff0000, v85
	v_lshlrev_b32_e32 v70, 16, v85
	v_pk_add_f32 v[68:69], v[68:69], v[70:71]
	v_and_b32_e32 v71, 0xffff0000, v89
	v_lshlrev_b32_e32 v70, 16, v89
	v_pk_add_f32 v[68:69], v[68:69], v[70:71]
	v_and_b32_e32 v71, 0xffff0000, v173
	v_lshlrev_b32_e32 v70, 16, v173
	v_pk_add_f32 v[68:69], v[68:69], v[70:71]
	v_and_b32_e32 v71, 0xffff0000, v177
	v_lshlrev_b32_e32 v70, 16, v177
	v_pk_add_f32 v[68:69], v[68:69], v[70:71]
	v_and_b32_e32 v71, 0xffff0000, v181
	v_lshlrev_b32_e32 v70, 16, v181
	v_pk_add_f32 v[68:69], v[68:69], v[70:71]
	v_and_b32_e32 v71, 0xffff0000, v195
	v_lshlrev_b32_e32 v70, 16, v195
	v_pk_add_f32 v[68:69], v[68:69], v[70:71]
	v_and_b32_e32 v71, 0xffff0000, v67
	v_lshlrev_b32_e32 v70, 16, v67
	v_pk_fma_f32 v[68:69], v[110:111], v[68:69], v[70:71] neg_lo:[0,0,1] neg_hi:[0,0,1]
	v_add_co_u32_e32 v170, vcc, s5, v166
	v_cvt_pk_bf16_f32 v67, v68, v69
	global_load_dwordx4 v[216:219], v[168:169], off offset:-4096
	v_addc_co_u32_e32 v171, vcc, 0, v167, vcc
	s_mov_b32 s5, 0x1d000
	global_load_dwordx4 v[220:223], v[168:169], off
	v_add_co_u32_e32 v172, vcc, s5, v166
	global_load_dwordx4 v[224:227], v[170:171], off offset:-4096
	v_addc_co_u32_e32 v173, vcc, 0, v167, vcc
	global_load_dwordx4 v[228:231], v[170:171], off
	s_mov_b32 s5, 0x1f000
	v_add_co_u32_e32 v166, vcc, s5, v166
	global_load_dwordx4 v[232:235], v[172:173], off offset:-4096
	v_addc_co_u32_e32 v167, vcc, 0, v167, vcc
	global_load_dwordx4 v[236:239], v[172:173], off
	global_load_dwordx4 v[240:243], v[166:167], off offset:-4096
	global_load_dwordx4 v[244:247], v[166:167], off
	s_waitcnt vmcnt(7)
	v_mfma_f32_16x16x32_bf16 v[60:63], v[64:67], v[216:219], v[60:63]
	s_waitcnt vmcnt(6)
; __device__ __forceinline__ float bf2f(bfr h) { return __uint_as_float(((unsigned)h) << 16); }
; template <int W>
; __device__ __forceinline__ void pool_tile(const Params& p, int row0, int g, int wave, int lane_in) {
;     ...
; #pragma unroll
;     for (int m = 0; m < 2; m++) {
;       int tt = t0 + wave * 32 + m * 16 + fr;
;       int lo = max(tt - W / 2, 0), hi = min(tt + W - W / 2, S);
;       float sum[8];
; #pragma unroll
;       for (int e = 0; e < 8; e++) sum[e] = 0.f;
;       const bfr* colp = xp + (size_t)b * S * 512 + g * 128 + ks * 32 + fq * 8;
;       constexpr int WC = W < 8 ? W : 8;
;       bf16x8 xc = *(const bf16x8*)(colp + (size_t)tt * 512);
; #pragma unroll
;       for (int o0 = 0; o0 < W; o0 += WC) {
;         bf16x8 wv[WC];
; #pragma unroll
;         for (int o = 0; o < WC; o++) {
;           int rc = min(max(tt - W / 2 + o0 + o, 0), S - 1);
;           wv[o] = *(const bf16x8*)(colp + (size_t)rc * 512);
;         }
; #pragma unroll
;         for (int o = 0; o < WC; o++) {
;           int r = tt - W / 2 + o0 + o;
;           float wgt = (r >= 0 && r < S) ? 1.f : 0.f;
; #pragma unroll
;           for (int e = 0; e < 8; e++) sum[e] += wgt * bf2f((bfr)wv[o][e]);
;         }
;         __builtin_amdgcn_sched_barrier(0);
;       }
;       float invn = 1.f / (float)(hi - lo);
;       u32x4 pk;
; #pragma unroll
;       for (int e = 0; e < 4; e++)
;         pk[e] = pack2(sum[2 * e] * invn - bf2f((bfr)xc[2 * e]), sum[2 * e + 1] * invn - bf2f((bfr)xc[2 * e + 1]));
;       bf16x8 af = __builtin_bit_cast(bf16x8, pk);
; #pragma unroll
;       for (int n = 0; n < 8; n++) {
;         bf16x8 bfg = *(const bf16x8*)(wp + (size_t)(n * 16 + fr) * 128 + ks * 32 + fq * 8);
;         acc[m][n] = mfma16(af, bfg, acc[m][n]);
;       }
	v_mfma_f32_16x16x32_bf16 v[52:55], v[64:67], v[220:223], v[52:55]
	s_waitcnt vmcnt(5)
	v_mfma_f32_16x16x32_bf16 v[44:47], v[64:67], v[224:227], v[44:47]
	s_waitcnt vmcnt(4)
	v_mfma_f32_16x16x32_bf16 v[36:39], v[64:67], v[228:231], v[36:39]
	s_waitcnt vmcnt(3)
	v_mfma_f32_16x16x32_bf16 v[28:31], v[64:67], v[232:235], v[28:31]
	s_waitcnt vmcnt(2)
	v_mfma_f32_16x16x32_bf16 v[20:23], v[64:67], v[236:239], v[20:23]
	s_waitcnt vmcnt(1)
	v_mfma_f32_16x16x32_bf16 v[12:15], v[64:67], v[240:243], v[12:15]
	s_waitcnt vmcnt(0)
	v_mfma_f32_16x16x32_bf16 v[4:7], v[64:67], v[244:247], v[4:7]
	v_add_co_u32_e32 v68, vcc, s87, v164
	v_lshl_add_u64 v[88:89], v[142:143], 0, s[36:37]
	s_nop 0
	v_addc_co_u32_e32 v69, vcc, 0, v165, vcc
	global_load_dwordx4 v[64:67], v[88:89], off
	global_load_dwordx4 v[176:179], v[68:69], off offset:768
	global_load_dwordx4 v[192:195], v[68:69], off offset:1792
	global_load_dwordx4 v[196:199], v[68:69], off offset:2816
	global_load_dwordx4 v[80:83], v[68:69], off offset:3840
	v_add_co_u32_e32 v68, vcc, s90, v164
	s_waitcnt vmcnt(3)
	v_and_b32_e32 v91, 0xffff0000, v176
	v_addc_co_u32_e32 v69, vcc, 0, v165, vcc
	global_load_dwordx4 v[84:87], v[68:69], off offset:768
	global_load_dwordx4 v[76:79], v[68:69], off offset:1792
	global_load_dwordx4 v[72:75], v[68:69], off offset:2816
	s_nop 0
	global_load_dwordx4 v[68:71], v[68:69], off offset:3840
	v_lshlrev_b32_e32 v90, 16, v176
	v_pk_add_f32 v[90:91], v[90:91], 0 op_sel_hi:[1,0]
	s_waitcnt vmcnt(6)
	v_and_b32_e32 v165, 0xffff0000, v192
	v_lshlrev_b32_e32 v164, 16, v192
	v_pk_add_f32 v[90:91], v[90:91], v[164:165]
	s_waitcnt vmcnt(5)
	v_and_b32_e32 v165, 0xffff0000, v196
	v_lshlrev_b32_e32 v164, 16, v196
	v_pk_add_f32 v[90:91], v[90:91], v[164:165]
	s_waitcnt vmcnt(4)
	v_and_b32_e32 v165, 0xffff0000, v80
	v_lshlrev_b32_e32 v164, 16, v80
	v_pk_add_f32 v[90:91], v[90:91], v[164:165]
	s_waitcnt vmcnt(3)
	v_and_b32_e32 v165, 0xffff0000, v84
	v_lshlrev_b32_e32 v164, 16, v84
	v_pk_add_f32 v[90:91], v[90:91], v[164:165]
	s_waitcnt vmcnt(2)
	v_and_b32_e32 v165, 0xffff0000, v76
	v_lshlrev_b32_e32 v164, 16, v76
	v_pk_add_f32 v[90:91], v[90:91], v[164:165]
	s_waitcnt vmcnt(1)
	v_and_b32_e32 v165, 0xffff0000, v72
	v_lshlrev_b32_e32 v164, 16, v72
	v_pk_add_f32 v[174:175], v[90:91], v[164:165]
	v_and_b32_e32 v91, 0xffff0000, v177
	v_lshlrev_b32_e32 v90, 16, v177
	v_pk_add_f32 v[90:91], v[90:91], 0 op_sel_hi:[1,0]
	v_and_b32_e32 v165, 0xffff0000, v193
	v_lshlrev_b32_e32 v164, 16, v193
	v_pk_add_f32 v[90:91], v[90:91], v[164:165]
	v_and_b32_e32 v165, 0xffff0000, v197
	v_lshlrev_b32_e32 v164, 16, v197
	v_pk_add_f32 v[90:91], v[90:91], v[164:165]
	v_and_b32_e32 v165, 0xffff0000, v81
	v_lshlrev_b32_e32 v164, 16, v81
	v_pk_add_f32 v[80:81], v[90:91], v[164:165]
	v_and_b32_e32 v91, 0xffff0000, v85
	v_lshlrev_b32_e32 v90, 16, v85
	v_pk_add_f32 v[80:81], v[80:81], v[90:91]
	v_and_b32_e32 v85, 0xffff0000, v77
	v_lshlrev_b32_e32 v84, 16, v77
	v_pk_add_f32 v[76:77], v[80:81], v[84:85]
	v_and_b32_e32 v81, 0xffff0000, v73
	v_lshlrev_b32_e32 v80, 16, v73
	v_and_b32_e32 v73, 0xffff0000, v178
	v_lshlrev_b32_e32 v72, 16, v178
	v_pk_add_f32 v[176:177], v[76:77], v[80:81]
	v_pk_add_f32 v[72:73], v[72:73], 0 op_sel_hi:[1,0]
	v_and_b32_e32 v77, 0xffff0000, v194
	v_lshlrev_b32_e32 v76, 16, v194
	v_pk_add_f32 v[72:73], v[72:73], v[76:77]
	v_and_b32_e32 v77, 0xffff0000, v198
	v_lshlrev_b32_e32 v76, 16, v198
	v_pk_add_f32 v[72:73], v[72:73], v[76:77]
	v_and_b32_e32 v77, 0xffff0000, v82
	v_lshlrev_b32_e32 v76, 16, v82
	v_pk_add_f32 v[72:73], v[72:73], v[76:77]
	v_and_b32_e32 v77, 0xffff0000, v86
	v_lshlrev_b32_e32 v76, 16, v86
	v_pk_add_f32 v[72:73], v[72:73], v[76:77]
	v_and_b32_e32 v77, 0xffff0000, v78
	v_lshlrev_b32_e32 v76, 16, v78
	v_pk_add_f32 v[72:73], v[72:73], v[76:77]
	v_and_b32_e32 v77, 0xffff0000, v74
	v_lshlrev_b32_e32 v76, 16, v74
	v_pk_add_f32 v[164:165], v[72:73], v[76:77]
	v_and_b32_e32 v73, 0xffff0000, v179
	v_lshlrev_b32_e32 v72, 16, v179
	v_pk_add_f32 v[72:73], v[72:73], 0 op_sel_hi:[1,0]
	v_and_b32_e32 v77, 0xffff0000, v195
	v_lshlrev_b32_e32 v76, 16, v195
	v_pk_add_f32 v[72:73], v[72:73], v[76:77]
	v_and_b32_e32 v77, 0xffff0000, v199
	v_lshlrev_b32_e32 v76, 16, v199
	v_pk_add_f32 v[72:73], v[72:73], v[76:77]
	v_and_b32_e32 v77, 0xffff0000, v83
	v_lshlrev_b32_e32 v76, 16, v83
	v_pk_add_f32 v[72:73], v[72:73], v[76:77]
	v_and_b32_e32 v77, 0xffff0000, v87
	v_lshlrev_b32_e32 v76, 16, v87
	v_pk_add_f32 v[72:73], v[72:73], v[76:77]
	v_and_b32_e32 v77, 0xffff0000, v79
	v_lshlrev_b32_e32 v76, 16, v79
	v_pk_add_f32 v[72:73], v[72:73], v[76:77]
	v_and_b32_e32 v77, 0xffff0000, v75
	v_lshlrev_b32_e32 v76, 16, v75
	v_pk_add_f32 v[178:179], v[72:73], v[76:77]
	s_waitcnt vmcnt(0)
	v_and_b32_e32 v201, 0xffff0000, v68
	v_lshlrev_b32_e32 v200, 16, v68
	v_and_b32_e32 v203, 0xffff0000, v69
	v_lshlrev_b32_e32 v202, 16, v69
	v_and_b32_e32 v205, 0xffff0000, v70
	v_lshlrev_b32_e32 v204, 16, v70
	v_and_b32_e32 v181, 0xffff0000, v71
	v_lshlrev_b32_e32 v180, 16, v71
	v_lshl_add_u64 v[68:69], v[140:141], 0, s[36:37]
	global_load_dwordx4 v[192:195], v[88:89], off
	global_load_dwordx4 v[196:199], v[68:69], off
	v_lshl_add_u64 v[70:71], v[138:139], 0, s[36:37]
	v_lshl_add_u64 v[72:73], v[136:137], 0, s[36:37]
	v_lshl_add_u64 v[74:75], v[134:135], 0, s[36:37]
	v_lshl_add_u64 v[76:77], v[132:133], 0, s[36:37]
	v_lshl_add_u64 v[68:69], v[130:131], 0, s[36:37]
	v_lshl_add_u64 v[206:207], v[128:129], 0, s[36:37]
	global_load_dwordx4 v[88:91], v[70:71], off
	global_load_dwordx4 v[84:87], v[72:73], off
	global_load_dwordx4 v[80:83], v[74:75], off
	s_nop 0
	global_load_dwordx4 v[76:79], v[76:77], off
	s_nop 0
	global_load_dwordx4 v[72:75], v[68:69], off
	s_nop 0
	global_load_dwordx4 v[68:71], v[206:207], off
	s_waitcnt vmcnt(7)
; __device__ __forceinline__ float bf2f(bfr h) { return __uint_as_float(((unsigned)h) << 16); }
; template <int W>
; __device__ __forceinline__ void pool_tile(const Params& p, int row0, int g, int wave, int lane_in) {
;     ...
;       const bfr* colp = xp + (size_t)b * S * 512 + g * 128 + ks * 32 + fq * 8;
;       constexpr int WC = W < 8 ? W : 8;
;       bf16x8 xc = *(const bf16x8*)(colp + (size_t)tt * 512);
; #pragma unroll
;       for (int o0 = 0; o0 < W; o0 += WC) {
;         bf16x8 wv[WC];
; #pragma unroll
;         for (int o = 0; o < WC; o++) {
;           int rc = min(max(tt - W / 2 + o0 + o, 0), S - 1);
;           wv[o] = *(const bf16x8*)(colp + (size_t)rc * 512);
;         }
; #pragma unroll
;         for (int o = 0; o < WC; o++) {
;           int r = tt - W / 2 + o0 + o;
;           float wgt = (r >= 0 && r < S) ? 1.f : 0.f;
; #pragma unroll
;           for (int e = 0; e < 8; e++) sum[e] += wgt * bf2f((bfr)wv[o][e]);
;         }
;         __builtin_amdgcn_sched_barrier(0);
;       }
;       float invn = 1.f / (float)(hi - lo);
;       u32x4 pk;
; #pragma unroll
;       for (int e = 0; e < 4; e++)
;         pk[e] = pack2(sum[2 * e] * invn - bf2f((bfr)xc[2 * e]), sum[2 * e + 1] * invn - bf2f((bfr)xc[2 * e + 1]));
;       bf16x8 af = __builtin_bit_cast(bf16x8, pk);
; #pragma unroll
;       for (int n = 0; n < 8; n++) {
;         bf16x8 bfg = *(const bf16x8*)(wp + (size_t)(n * 16 + fr) * 128 + ks * 32 + fq * 8);
;         acc[m][n] = mfma16(af, bfg, acc[m][n]);
;       }
;       __builtin_amdgcn_sched_barrier(0);
	v_and_b32_e32 v207, 0xffff0000, v192
	v_lshlrev_b32_e32 v206, 16, v192
	v_and_b32_e32 v209, 0xffff0000, v193
	v_lshlrev_b32_e32 v208, 16, v193
	v_and_b32_e32 v211, 0xffff0000, v194
	v_lshlrev_b32_e32 v210, 16, v194
	v_and_b32_e32 v213, 0xffff0000, v195
	v_lshlrev_b32_e32 v212, 16, v195
	s_waitcnt vmcnt(6)
	v_and_b32_e32 v193, 0xffff0000, v196
	v_lshlrev_b32_e32 v192, 16, v196
	v_and_b32_e32 v195, 0xffff0000, v197
	v_lshlrev_b32_e32 v194, 16, v197
	v_and_b32_e32 v197, 0xffff0000, v198
	v_lshlrev_b32_e32 v196, 16, v198
	v_and_b32_e32 v215, 0xffff0000, v199
	v_lshlrev_b32_e32 v214, 16, v199
	v_pk_add_f32 v[174:175], v[174:175], v[200:201]
	s_waitcnt vmcnt(5)
	v_and_b32_e32 v201, 0xffff0000, v89
	v_pk_add_f32 v[174:175], v[174:175], v[206:207]
	v_lshlrev_b32_e32 v200, 16, v89
	v_pk_fma_f32 v[174:175], v[112:113], v[192:193], v[174:175]
	v_and_b32_e32 v193, 0xffff0000, v88
	v_lshlrev_b32_e32 v192, 16, v88
	v_pk_fma_f32 v[174:175], v[114:115], v[192:193], v[174:175]
	s_waitcnt vmcnt(4)
	v_and_b32_e32 v193, 0xffff0000, v84
	v_lshlrev_b32_e32 v192, 16, v84
	v_pk_fma_f32 v[174:175], v[116:117], v[192:193], v[174:175]
	s_waitcnt vmcnt(3)
	v_and_b32_e32 v193, 0xffff0000, v80
	v_lshlrev_b32_e32 v192, 16, v80
	v_pk_fma_f32 v[174:175], v[118:119], v[192:193], v[174:175]
	s_waitcnt vmcnt(2)
	v_and_b32_e32 v193, 0xffff0000, v76
	v_lshlrev_b32_e32 v192, 16, v76
	v_pk_fma_f32 v[174:175], v[120:121], v[192:193], v[174:175]
	s_waitcnt vmcnt(1)
	v_and_b32_e32 v193, 0xffff0000, v72
	v_lshlrev_b32_e32 v192, 16, v72
	v_pk_fma_f32 v[174:175], v[122:123], v[192:193], v[174:175]
	s_waitcnt vmcnt(0)
	v_and_b32_e32 v193, 0xffff0000, v68
	v_lshlrev_b32_e32 v192, 16, v68
	v_pk_fma_f32 v[174:175], v[124:125], v[192:193], v[174:175]
	v_and_b32_e32 v193, 0xffff0000, v64
	v_lshlrev_b32_e32 v192, 16, v64
	v_pk_fma_f32 v[174:175], v[126:127], v[174:175], v[192:193] neg_lo:[0,0,1] neg_hi:[0,0,1]
	v_pk_add_f32 v[192:193], v[176:177], v[202:203]
	v_cvt_pk_bf16_f32 v64, v174, v175
	v_pk_add_f32 v[192:193], v[192:193], v[208:209]
	global_load_dwordx4 v[174:177], v[168:169], off offset:-4096
	v_pk_fma_f32 v[198:199], v[112:113], v[194:195], v[192:193]
	global_load_dwordx4 v[192:195], v[168:169], off
	v_pk_fma_f32 v[88:89], v[114:115], v[200:201], v[198:199]
	v_and_b32_e32 v169, 0xffff0000, v85
	v_lshlrev_b32_e32 v168, 16, v85
	v_pk_fma_f32 v[84:85], v[116:117], v[168:169], v[88:89]
	v_and_b32_e32 v89, 0xffff0000, v81
	v_lshlrev_b32_e32 v88, 16, v81
	v_pk_fma_f32 v[80:81], v[118:119], v[88:89], v[84:85]
	v_and_b32_e32 v85, 0xffff0000, v77
	v_lshlrev_b32_e32 v84, 16, v77
	v_pk_fma_f32 v[76:77], v[120:121], v[84:85], v[80:81]
	v_and_b32_e32 v81, 0xffff0000, v73
	v_lshlrev_b32_e32 v80, 16, v73
	v_pk_fma_f32 v[72:73], v[122:123], v[80:81], v[76:77]
	v_and_b32_e32 v77, 0xffff0000, v69
	v_lshlrev_b32_e32 v76, 16, v69
	v_pk_fma_f32 v[68:69], v[124:125], v[76:77], v[72:73]
	v_and_b32_e32 v73, 0xffff0000, v65
	v_lshlrev_b32_e32 v72, 16, v65
	v_pk_fma_f32 v[68:69], v[126:127], v[68:69], v[72:73] neg_lo:[0,0,1] neg_hi:[0,0,1]
	v_and_b32_e32 v73, 0xffff0000, v90
	v_cvt_pk_bf16_f32 v65, v68, v69
	v_pk_add_f32 v[68:69], v[164:165], v[204:205]
	v_lshlrev_b32_e32 v72, 16, v90
	v_pk_add_f32 v[68:69], v[68:69], v[210:211]
	s_nop 0
	v_pk_fma_f32 v[68:69], v[112:113], v[196:197], v[68:69]
	s_nop 0
	v_pk_fma_f32 v[68:69], v[114:115], v[72:73], v[68:69]
	v_and_b32_e32 v73, 0xffff0000, v86
	v_lshlrev_b32_e32 v72, 16, v86
	v_pk_fma_f32 v[68:69], v[116:117], v[72:73], v[68:69]
	v_and_b32_e32 v73, 0xffff0000, v82
	v_lshlrev_b32_e32 v72, 16, v82
	v_pk_fma_f32 v[68:69], v[118:119], v[72:73], v[68:69]
	v_and_b32_e32 v73, 0xffff0000, v78
	v_lshlrev_b32_e32 v72, 16, v78
	v_pk_fma_f32 v[68:69], v[120:121], v[72:73], v[68:69]
	v_and_b32_e32 v73, 0xffff0000, v74
	v_lshlrev_b32_e32 v72, 16, v74
	v_pk_fma_f32 v[68:69], v[122:123], v[72:73], v[68:69]
	v_and_b32_e32 v73, 0xffff0000, v70
	v_lshlrev_b32_e32 v72, 16, v70
	v_pk_fma_f32 v[68:69], v[124:125], v[72:73], v[68:69]
	v_and_b32_e32 v73, 0xffff0000, v66
	v_lshlrev_b32_e32 v72, 16, v66
	v_pk_fma_f32 v[68:69], v[126:127], v[68:69], v[72:73] neg_lo:[0,0,1] neg_hi:[0,0,1]
	v_and_b32_e32 v73, 0xffff0000, v91
	v_cvt_pk_bf16_f32 v66, v68, v69
	v_pk_add_f32 v[68:69], v[178:179], v[180:181]
	v_lshlrev_b32_e32 v72, 16, v91
	v_pk_add_f32 v[68:69], v[68:69], v[212:213]
	v_lshlrev_b32_e32 v70, 16, v67
	v_pk_fma_f32 v[68:69], v[112:113], v[214:215], v[68:69]
	s_nop 0
	v_pk_fma_f32 v[68:69], v[114:115], v[72:73], v[68:69]
	v_and_b32_e32 v73, 0xffff0000, v87
	v_lshlrev_b32_e32 v72, 16, v87
	v_pk_fma_f32 v[68:69], v[116:117], v[72:73], v[68:69]
	v_and_b32_e32 v73, 0xffff0000, v83
	v_lshlrev_b32_e32 v72, 16, v83
	v_pk_fma_f32 v[68:69], v[118:119], v[72:73], v[68:69]
	v_and_b32_e32 v73, 0xffff0000, v79
	v_lshlrev_b32_e32 v72, 16, v79
	v_pk_fma_f32 v[68:69], v[120:121], v[72:73], v[68:69]
	v_and_b32_e32 v73, 0xffff0000, v75
	v_lshlrev_b32_e32 v72, 16, v75
	v_pk_fma_f32 v[68:69], v[122:123], v[72:73], v[68:69]
	v_and_b32_e32 v73, 0xffff0000, v71
	v_lshlrev_b32_e32 v72, 16, v71
	v_pk_fma_f32 v[68:69], v[124:125], v[72:73], v[68:69]
	v_and_b32_e32 v71, 0xffff0000, v67
	v_pk_fma_f32 v[68:69], v[126:127], v[68:69], v[70:71] neg_lo:[0,0,1] neg_hi:[0,0,1]
	global_load_dwordx4 v[72:75], v[170:171], off
	v_cvt_pk_bf16_f32 v67, v68, v69
	global_load_dwordx4 v[68:71], v[170:171], off offset:-4096
	s_waitcnt vmcnt(3)
	v_mfma_f32_16x16x32_bf16 v[56:59], v[64:67], v[174:177], v[56:59]
	s_waitcnt vmcnt(2)
	v_mfma_f32_16x16x32_bf16 v[48:51], v[64:67], v[192:195], v[48:51]
	s_waitcnt vmcnt(0)
	v_mfma_f32_16x16x32_bf16 v[40:43], v[64:67], v[68:71], v[40:43]
	global_load_dwordx4 v[68:71], v[172:173], off offset:-4096
	v_mfma_f32_16x16x32_bf16 v[32:35], v[64:67], v[72:75], v[32:35]
	global_load_dwordx4 v[72:75], v[172:173], off
	s_waitcnt vmcnt(1)
	v_mfma_f32_16x16x32_bf16 v[24:27], v[64:67], v[68:71], v[24:27]
	global_load_dwordx4 v[68:71], v[166:167], off offset:-4096
	s_waitcnt vmcnt(1)
	v_mfma_f32_16x16x32_bf16 v[16:19], v[64:67], v[72:75], v[16:19]
	global_load_dwordx4 v[72:75], v[166:167], off
	s_waitcnt vmcnt(1)
	v_mfma_f32_16x16x32_bf16 v[8:11], v[64:67], v[68:71], v[8:11]
	s_waitcnt vmcnt(0)
	v_mfma_f32_16x16x32_bf16 v[0:3], v[64:67], v[72:75], v[0:3]
	s_add_u32 s36, s36, 64
	s_addc_u32 s37, s37, 0
	s_cmpk_lg_i32 s36, 0x100
	s_cbranch_scc1 .LBB0_1155
; template <int W>
; __device__ __forceinline__ void pool_tile(const Params& p, int row0, int g, int wave, int lane_in) {
;     ...
; #pragma unroll
;   for (int n = 0; n < 8; n++) {
;     float cs = p.c_scale[g * 128 + n * 16 + fr];
; #pragma unroll
;     for (int m = 0; m < 2; m++)
; #pragma unroll
;       for (int j = 0; j < 4; j++) {
;         size_t row = (size_t)row0 + wave * 32 + m * 16 + fq * 4 + j;
;         p.mix[row * D + g * 128 + n * 16 + fr] = f2bf(acc[m][n][j] * cs);
;       }
;   }
	s_ashr_i32 s55, s54, 31
	v_lshlrev_b32_e32 v64, 2, v191
	v_readlane_b32 s60, v255, 10
	s_or_b64 s[36:37], s[54:55], s[0:1]
	v_ashrrev_i32_e32 v65, 31, v64
	v_lshlrev_b32_e32 v92, 1, v190
	v_readlane_b32 s61, v255, 11
	v_readlane_b32 s62, v255, 12
	v_readlane_b32 s63, v255, 13
	v_readlane_b32 s64, v255, 14
	v_readlane_b32 s65, v255, 15
	v_readlane_b32 s66, v255, 16
	v_readlane_b32 s67, v255, 17
	v_readlane_b32 s68, v255, 18
	v_readlane_b32 s69, v255, 19
	v_readlane_b32 s70, v255, 20
	v_readlane_b32 s71, v255, 21
	v_readlane_b32 s72, v255, 22
	v_readlane_b32 s73, v255, 23
	v_readlane_b32 s74, v255, 24
	v_readlane_b32 s75, v255, 25
	v_lshl_add_u64 v[66:67], s[36:37], 0, v[64:65]
	v_lshl_add_u64 v[64:65], s[68:69], 0, v[92:93]
	v_readlane_b32 s60, v254, 38
	v_lshlrev_b32_e32 v72, 2, v190
	v_readlane_b32 s68, v254, 46
	v_readlane_b32 s69, v254, 47
	v_lshlrev_b64 v[74:75], 11, v[66:67]
	v_lshl_add_u64 v[66:67], v[64:65], 0, v[74:75]
	s_mov_b64 s[36:37], 0
	v_readlane_b32 s61, v254, 39
	v_readlane_b32 s62, v254, 40
	global_load_dword v73, v72, s[68:69] offset:1536
	v_readlane_b32 s63, v254, 41
	v_readlane_b32 s64, v254, 42
	v_readlane_b32 s65, v254, 43
	v_readlane_b32 s66, v254, 44
	v_readlane_b32 s67, v254, 45
	v_readlane_b32 s70, v254, 48
	v_readlane_b32 s71, v254, 49
	v_readlane_b32 s72, v254, 50
	v_readlane_b32 s73, v254, 51
	v_readlane_b32 s74, v254, 52
	v_readlane_b32 s75, v254, 53
	s_waitcnt vmcnt(0)
	v_mul_f32_e32 v60, v60, v73
	v_cvt_pk_bf16_f32 v60, v60, s0
	global_store_short v[66:67], v60, off offset:768
	v_mul_f32_e32 v60, v61, v73
	v_cvt_pk_bf16_f32 v60, v60, s0
	global_store_short v[66:67], v60, off offset:2816
	v_mul_f32_e32 v60, v62, v73
	v_cvt_pk_bf16_f32 v62, v60, s0
	v_or_b32_e32 v60, 0x1000, v74
	v_mov_b32_e32 v61, v75
	v_lshl_add_u64 v[68:69], v[64:65], 0, v[60:61]
	global_store_short v[68:69], v62, off offset:768
	v_mul_f32_e32 v62, v63, v73
	v_cvt_pk_bf16_f32 v70, v62, s0
	v_or_b32_e32 v62, 0x1800, v74
	v_mov_b32_e32 v63, v75
	v_lshl_add_u64 v[68:69], v[64:65], 0, v[62:63]
	global_store_short v[68:69], v70, off offset:768
	v_mul_f32_e32 v56, v56, v73
	v_add_co_u32_e32 v70, vcc, s91, v66
	v_cvt_pk_bf16_f32 v56, v56, s0
	s_nop 0
	v_addc_co_u32_e32 v71, vcc, 0, v67, vcc
	global_store_short v[70:71], v56, off offset:768
	v_mul_f32_e32 v56, v57, v73
	v_cvt_pk_bf16_f32 v76, v56, s0
	global_store_short v[70:71], v76, off offset:2816
	v_mul_f32_e32 v58, v58, v73
	v_add_co_u32_e32 v76, vcc, s92, v66
	v_cvt_pk_bf16_f32 v58, v58, s0
	s_nop 0
	v_addc_co_u32_e32 v77, vcc, 0, v67, vcc
	global_store_short v[76:77], v58, off offset:768
	v_mul_f32_e32 v58, v59, v73
	v_cvt_pk_bf16_f32 v73, v58, s0
	global_store_short v[76:77], v73, off offset:2816
	global_load_dword v73, v72, s[68:69] offset:1600
	v_lshl_add_u64 v[68:69], v[74:75], 0, s[30:31]
	v_lshl_add_u64 v[56:57], v[74:75], 0, s[34:35]
	v_lshl_add_u64 v[70:71], v[74:75], 0, s[38:39]
	v_lshl_add_u64 v[58:59], v[74:75], 0, s[40:41]
	v_lshl_add_u64 v[74:75], v[64:65], 0, 32
	s_waitcnt vmcnt(0)
	v_mul_f32_e32 v52, v52, v73
	v_cvt_pk_bf16_f32 v52, v52, s0
	global_store_short v[66:67], v52, off offset:800
	v_mul_f32_e32 v52, v53, v73
	v_cvt_pk_bf16_f32 v52, v52, s0
	global_store_short v[66:67], v52, off offset:2848
	v_mul_f32_e32 v52, v54, v73
	v_cvt_pk_bf16_f32 v54, v52, s0
	v_lshl_add_u64 v[52:53], v[74:75], 0, v[60:61]
	global_store_short v[52:53], v54, off offset:768
	v_mul_f32_e32 v52, v55, v73
	v_cvt_pk_bf16_f32 v54, v52, s0
	v_lshl_add_u64 v[52:53], v[74:75], 0, v[62:63]
	v_mul_f32_e32 v48, v48, v73
	global_store_short v[52:53], v54, off offset:768
	v_cvt_pk_bf16_f32 v48, v48, s0
	v_lshl_add_u64 v[52:53], v[74:75], 0, v[68:69]
	global_store_short v[52:53], v48, off offset:768
	v_mul_f32_e32 v48, v49, v73
	v_cvt_pk_bf16_f32 v52, v48, s0
	v_lshl_add_u64 v[48:49], v[74:75], 0, v[56:57]
	global_store_short v[48:49], v52, off offset:768
	v_mul_f32_e32 v48, v50, v73
	v_cvt_pk_bf16_f32 v50, v48, s0
	v_lshl_add_u64 v[48:49], v[74:75], 0, v[70:71]
	global_store_short v[48:49], v50, off offset:768
	v_mul_f32_e32 v48, v51, v73
	v_cvt_pk_bf16_f32 v50, v48, s0
	v_lshl_add_u64 v[48:49], v[74:75], 0, v[58:59]
	global_store_short v[48:49], v50, off offset:768
	global_load_dword v50, v72, s[68:69] offset:1664
	v_lshl_add_u64 v[48:49], v[64:65], 0, 64
	s_waitcnt vmcnt(0)
	v_mul_f32_e32 v44, v44, v50
	v_cvt_pk_bf16_f32 v44, v44, s0
	global_store_short v[66:67], v44, off offset:832
	v_mul_f32_e32 v44, v45, v50
	v_cvt_pk_bf16_f32 v44, v44, s0
	global_store_short v[66:67], v44, off offset:2880
	v_mul_f32_e32 v44, v46, v50
	v_cvt_pk_bf16_f32 v46, v44, s0
	v_lshl_add_u64 v[44:45], v[48:49], 0, v[60:61]
	global_store_short v[44:45], v46, off offset:768
	v_mul_f32_e32 v44, v47, v50
	v_cvt_pk_bf16_f32 v46, v44, s0
	v_lshl_add_u64 v[44:45], v[48:49], 0, v[62:63]
	v_mul_f32_e32 v40, v40, v50
	global_store_short v[44:45], v46, off offset:768
	v_cvt_pk_bf16_f32 v40, v40, s0
	v_lshl_add_u64 v[44:45], v[48:49], 0, v[68:69]
	global_store_short v[44:45], v40, off offset:768
	v_mul_f32_e32 v40, v41, v50
	v_cvt_pk_bf16_f32 v44, v40, s0
	v_lshl_add_u64 v[40:41], v[48:49], 0, v[56:57]
	global_store_short v[40:41], v44, off offset:768
	v_mul_f32_e32 v40, v42, v50
	v_cvt_pk_bf16_f32 v42, v40, s0
	v_lshl_add_u64 v[40:41], v[48:49], 0, v[70:71]
	global_store_short v[40:41], v42, off offset:768
	v_mul_f32_e32 v40, v43, v50
	v_cvt_pk_bf16_f32 v42, v40, s0
	v_lshl_add_u64 v[40:41], v[48:49], 0, v[58:59]
	global_store_short v[40:41], v42, off offset:768
	global_load_dword v42, v72, s[68:69] offset:1728
	v_lshl_add_u64 v[40:41], v[64:65], 0, s[42:43]
	s_waitcnt vmcnt(0)
; template <int W>
; __device__ __forceinline__ void pool_tile(const Params& p, int row0, int g, int wave, int lane_in) {
;     ...
; #pragma unroll
;   for (int n = 0; n < 8; n++) {
;     float cs = p.c_scale[g * 128 + n * 16 + fr];
; #pragma unroll
;     for (int m = 0; m < 2; m++)
; #pragma unroll
;       for (int j = 0; j < 4; j++) {
;         size_t row = (size_t)row0 + wave * 32 + m * 16 + fq * 4 + j;
;         p.mix[row * D + g * 128 + n * 16 + fr] = f2bf(acc[m][n][j] * cs);
;       }
;   }
	v_mul_f32_e32 v36, v36, v42
	v_cvt_pk_bf16_f32 v36, v36, s0
	global_store_short v[66:67], v36, off offset:864
	v_mul_f32_e32 v36, v37, v42
	v_cvt_pk_bf16_f32 v36, v36, s0
	global_store_short v[66:67], v36, off offset:2912
	v_mul_f32_e32 v36, v38, v42
	v_cvt_pk_bf16_f32 v38, v36, s0
	v_lshl_add_u64 v[36:37], v[40:41], 0, v[60:61]
	global_store_short v[36:37], v38, off offset:768
	v_mul_f32_e32 v36, v39, v42
	v_cvt_pk_bf16_f32 v38, v36, s0
	v_lshl_add_u64 v[36:37], v[40:41], 0, v[62:63]
	v_mul_f32_e32 v32, v32, v42
	global_store_short v[36:37], v38, off offset:768
	v_cvt_pk_bf16_f32 v32, v32, s0
	v_lshl_add_u64 v[36:37], v[40:41], 0, v[68:69]
	global_store_short v[36:37], v32, off offset:768
	v_mul_f32_e32 v32, v33, v42
	v_cvt_pk_bf16_f32 v36, v32, s0
	v_lshl_add_u64 v[32:33], v[40:41], 0, v[56:57]
	global_store_short v[32:33], v36, off offset:768
	v_mul_f32_e32 v32, v34, v42
	v_cvt_pk_bf16_f32 v34, v32, s0
	v_lshl_add_u64 v[32:33], v[40:41], 0, v[70:71]
	global_store_short v[32:33], v34, off offset:768
	v_mul_f32_e32 v32, v35, v42
	v_cvt_pk_bf16_f32 v34, v32, s0
	v_lshl_add_u64 v[32:33], v[40:41], 0, v[58:59]
	global_store_short v[32:33], v34, off offset:768
	global_load_dword v34, v72, s[68:69] offset:1792
	v_lshl_add_u64 v[32:33], v[64:65], 0, s[44:45]
	s_waitcnt vmcnt(0)
	v_mul_f32_e32 v28, v28, v34
	v_cvt_pk_bf16_f32 v28, v28, s0
	global_store_short v[66:67], v28, off offset:896
	v_mul_f32_e32 v28, v29, v34
	v_cvt_pk_bf16_f32 v28, v28, s0
	global_store_short v[66:67], v28, off offset:2944
	v_mul_f32_e32 v28, v30, v34
	v_cvt_pk_bf16_f32 v30, v28, s0
	v_lshl_add_u64 v[28:29], v[32:33], 0, v[60:61]
	global_store_short v[28:29], v30, off offset:768
	v_mul_f32_e32 v28, v31, v34
	v_cvt_pk_bf16_f32 v30, v28, s0
	v_lshl_add_u64 v[28:29], v[32:33], 0, v[62:63]
	v_mul_f32_e32 v24, v24, v34
	global_store_short v[28:29], v30, off offset:768
	v_cvt_pk_bf16_f32 v24, v24, s0
	v_lshl_add_u64 v[28:29], v[32:33], 0, v[68:69]
	global_store_short v[28:29], v24, off offset:768
	v_mul_f32_e32 v24, v25, v34
	v_cvt_pk_bf16_f32 v28, v24, s0
	v_lshl_add_u64 v[24:25], v[32:33], 0, v[56:57]
	global_store_short v[24:25], v28, off offset:768
	v_mul_f32_e32 v24, v26, v34
	v_cvt_pk_bf16_f32 v26, v24, s0
	v_lshl_add_u64 v[24:25], v[32:33], 0, v[70:71]
	global_store_short v[24:25], v26, off offset:768
	v_mul_f32_e32 v24, v27, v34
	v_cvt_pk_bf16_f32 v26, v24, s0
	v_lshl_add_u64 v[24:25], v[32:33], 0, v[58:59]
	global_store_short v[24:25], v26, off offset:768
	global_load_dword v26, v72, s[68:69] offset:1856
	v_lshl_add_u64 v[24:25], v[64:65], 0, s[46:47]
	s_waitcnt vmcnt(0)
	v_mul_f32_e32 v20, v20, v26
	v_cvt_pk_bf16_f32 v20, v20, s0
	global_store_short v[66:67], v20, off offset:928
	v_mul_f32_e32 v20, v21, v26
	v_cvt_pk_bf16_f32 v20, v20, s0
	global_store_short v[66:67], v20, off offset:2976
	v_mul_f32_e32 v20, v22, v26
	v_cvt_pk_bf16_f32 v22, v20, s0
	v_lshl_add_u64 v[20:21], v[24:25], 0, v[60:61]
	global_store_short v[20:21], v22, off offset:768
	v_mul_f32_e32 v20, v23, v26
	v_cvt_pk_bf16_f32 v22, v20, s0
	v_lshl_add_u64 v[20:21], v[24:25], 0, v[62:63]
	v_mul_f32_e32 v16, v16, v26
	global_store_short v[20:21], v22, off offset:768
	v_cvt_pk_bf16_f32 v16, v16, s0
	v_lshl_add_u64 v[20:21], v[24:25], 0, v[68:69]
	global_store_short v[20:21], v16, off offset:768
	v_mul_f32_e32 v16, v17, v26
	v_cvt_pk_bf16_f32 v20, v16, s0
	v_lshl_add_u64 v[16:17], v[24:25], 0, v[56:57]
	global_store_short v[16:17], v20, off offset:768
	v_mul_f32_e32 v16, v18, v26
	v_cvt_pk_bf16_f32 v18, v16, s0
	v_lshl_add_u64 v[16:17], v[24:25], 0, v[70:71]
	global_store_short v[16:17], v18, off offset:768
	v_mul_f32_e32 v16, v19, v26
	v_cvt_pk_bf16_f32 v18, v16, s0
	v_lshl_add_u64 v[16:17], v[24:25], 0, v[58:59]
	global_store_short v[16:17], v18, off offset:768
	global_load_dword v18, v72, s[68:69] offset:1920
	v_lshl_add_u64 v[16:17], v[64:65], 0, s[48:49]
	s_waitcnt vmcnt(0)
	v_mul_f32_e32 v12, v12, v18
	v_cvt_pk_bf16_f32 v12, v12, s0
	global_store_short v[66:67], v12, off offset:960
	v_mul_f32_e32 v12, v13, v18
	v_cvt_pk_bf16_f32 v12, v12, s0
	global_store_short v[66:67], v12, off offset:3008
	v_mul_f32_e32 v12, v14, v18
	v_cvt_pk_bf16_f32 v14, v12, s0
	v_lshl_add_u64 v[12:13], v[16:17], 0, v[60:61]
	global_store_short v[12:13], v14, off offset:768
	v_mul_f32_e32 v12, v15, v18
	v_cvt_pk_bf16_f32 v14, v12, s0
	v_lshl_add_u64 v[12:13], v[16:17], 0, v[62:63]
	v_mul_f32_e32 v8, v8, v18
	global_store_short v[12:13], v14, off offset:768
	v_cvt_pk_bf16_f32 v8, v8, s0
	v_lshl_add_u64 v[12:13], v[16:17], 0, v[68:69]
	global_store_short v[12:13], v8, off offset:768
	v_mul_f32_e32 v8, v9, v18
	v_cvt_pk_bf16_f32 v12, v8, s0
	v_lshl_add_u64 v[8:9], v[16:17], 0, v[56:57]
	global_store_short v[8:9], v12, off offset:768
	v_mul_f32_e32 v8, v10, v18
	v_cvt_pk_bf16_f32 v10, v8, s0
	v_lshl_add_u64 v[8:9], v[16:17], 0, v[70:71]
	global_store_short v[8:9], v10, off offset:768
	v_mul_f32_e32 v8, v11, v18
	v_cvt_pk_bf16_f32 v10, v8, s0
	v_lshl_add_u64 v[8:9], v[16:17], 0, v[58:59]
	global_store_short v[8:9], v10, off offset:768
	global_load_dword v8, v72, s[68:69] offset:1984
	v_lshl_add_u64 v[10:11], v[64:65], 0, s[50:51]
	s_waitcnt vmcnt(0)
	v_mul_f32_e32 v4, v4, v8
	v_cvt_pk_bf16_f32 v4, v4, s0
	global_store_short v[66:67], v4, off offset:992
	v_mul_f32_e32 v4, v5, v8
	v_cvt_pk_bf16_f32 v4, v4, s0
	global_store_short v[66:67], v4, off offset:3040
	v_mul_f32_e32 v4, v6, v8
	v_cvt_pk_bf16_f32 v6, v4, s0
	v_lshl_add_u64 v[4:5], v[10:11], 0, v[60:61]
	global_store_short v[4:5], v6, off offset:768
	v_mul_f32_e32 v4, v7, v8
	v_cvt_pk_bf16_f32 v6, v4, s0
	v_lshl_add_u64 v[4:5], v[10:11], 0, v[62:63]
	v_mul_f32_e32 v0, v0, v8
	global_store_short v[4:5], v6, off offset:768
	v_cvt_pk_bf16_f32 v0, v0, s0
	v_lshl_add_u64 v[4:5], v[10:11], 0, v[68:69]
	global_store_short v[4:5], v0, off offset:768
	v_mul_f32_e32 v0, v1, v8
	v_cvt_pk_bf16_f32 v4, v0, s0
	v_lshl_add_u64 v[0:1], v[10:11], 0, v[56:57]
	global_store_short v[0:1], v4, off offset:768
	v_mul_f32_e32 v0, v2, v8
	v_cvt_pk_bf16_f32 v2, v0, s0
	v_lshl_add_u64 v[0:1], v[10:11], 0, v[70:71]
	global_store_short v[0:1], v2, off offset:768
	v_mul_f32_e32 v0, v3, v8
	v_cvt_pk_bf16_f32 v2, v0, s0
	v_lshl_add_u64 v[0:1], v[10:11], 0, v[58:59]
	global_store_short v[0:1], v2, off offset:768

; __device__ __forceinline__ float bf2f(bfr h) { return __uint_as_float(((unsigned)h) << 16); }
; template <int W>
; __device__ __forceinline__ void pool_tile(const Params& p, int row0, int g, int wave, int lane_in) {
;     ...
; #pragma unroll
;     for (int m = 0; m < 2; m++) {
;       int tt = t0 + wave * 32 + m * 16 + fr;
;       int lo = max(tt - W / 2, 0), hi = min(tt + W - W / 2, S);
;       float sum[8];
; #pragma unroll
;       for (int e = 0; e < 8; e++) sum[e] = 0.f;
;       const bfr* colp = xp + (size_t)b * S * 512 + g * 128 + ks * 32 + fq * 8;
;       constexpr int WC = W < 8 ? W : 8;
;       bf16x8 xc = *(const bf16x8*)(colp + (size_t)tt * 512);
; #pragma unroll
;       for (int o0 = 0; o0 < W; o0 += WC) {
;         bf16x8 wv[WC];
; #pragma unroll
;         for (int o = 0; o < WC; o++) {
;           int rc = min(max(tt - W / 2 + o0 + o, 0), S - 1);
;           wv[o] = *(const bf16x8*)(colp + (size_t)rc * 512);
;         }
; #pragma unroll
;         for (int o = 0; o < WC; o++) {
;           int r = tt - W / 2 + o0 + o;
;           float wgt = (r >= 0 && r < S) ? 1.f : 0.f;
; #pragma unroll
;           for (int e = 0; e < 8; e++) sum[e] += wgt * bf2f((bfr)wv[o][e]);
;         }
;         __builtin_amdgcn_sched_barrier(0);
;       }
;       float invn = 1.f / (float)(hi - lo);
;       u32x4 pk;
; #pragma unroll
;       for (int e = 0; e < 4; e++)
;         pk[e] = pack2(sum[2 * e] * invn - bf2f((bfr)xc[2 * e]), sum[2 * e + 1] * invn - bf2f((bfr)xc[2 * e + 1]));
;       bf16x8 af = __builtin_bit_cast(bf16x8, pk);
; #pragma unroll
;       for (int n = 0; n < 8; n++) {
;         bf16x8 bfg = *(const bf16x8*)(wp + (size_t)(n * 16 + fr) * 128 + ks * 32 + fq * 8);
;         acc[m][n] = mfma16(af, bfg, acc[m][n]);
;       }
.LBB0_1159:
	v_lshl_add_u64 v[64:65], v[104:105], 0, s[36:37]
	v_lshl_add_u64 v[108:109], v[102:103], 0, s[36:37]
	v_lshl_add_u64 v[112:113], v[100:101], 0, s[36:37]
	global_load_dwordx4 v[64:67], v[64:65], off
	v_lshl_add_u64 v[114:115], v[96:97], 0, s[36:37]
	global_load_dwordx4 v[108:111], v[108:109], off
	v_lshl_add_u64 v[116:117], v[98:99], 0, s[36:37]
	global_load_dwordx4 v[120:123], v[112:113], off
	global_load_dwordx4 v[124:127], v[116:117], off
	global_load_dwordx4 v[128:131], v[114:115], off offset:512
	global_load_dwordx4 v[132:135], v[114:115], off offset:1536
	global_load_dwordx4 v[136:139], v[114:115], off offset:2560
	global_load_dwordx4 v[140:143], v[114:115], off offset:3584
	v_lshl_add_u64 v[116:117], v[106:107], 0, s[36:37]
	s_waitcnt vmcnt(7)
	v_and_b32_e32 v113, 0xffff0000, v64
	v_lshlrev_b32_e32 v112, 16, v64
	v_and_b32_e32 v145, 0xffff0000, v65
	v_lshlrev_b32_e32 v144, 16, v65
	v_and_b32_e32 v147, 0xffff0000, v66
	v_lshlrev_b32_e32 v146, 16, v66
	v_and_b32_e32 v149, 0xffff0000, v67
	v_lshlrev_b32_e32 v148, 16, v67
	s_waitcnt vmcnt(6)
	v_and_b32_e32 v65, 0xffff0000, v108
	v_lshlrev_b32_e32 v64, 16, v108
	v_and_b32_e32 v67, 0xffff0000, v109
	v_lshlrev_b32_e32 v66, 16, v109
	v_and_b32_e32 v109, 0xffff0000, v110
	v_lshlrev_b32_e32 v108, 16, v110
	v_and_b32_e32 v151, 0xffff0000, v111
	v_lshlrev_b32_e32 v150, 16, v111
	v_pk_fma_f32 v[110:111], v[68:69], v[112:113], 0 op_sel_hi:[1,1,0]
	s_waitcnt vmcnt(2)
	v_and_b32_e32 v113, 0xffff0000, v132
	v_pk_fma_f32 v[64:65], v[70:71], v[64:65], v[110:111]
	v_and_b32_e32 v111, 0xffff0000, v120
	v_lshlrev_b32_e32 v110, 16, v120
	v_pk_fma_f32 v[64:65], v[72:73], v[110:111], v[64:65]
	v_and_b32_e32 v111, 0xffff0000, v124
	v_lshlrev_b32_e32 v110, 16, v124
	v_pk_fma_f32 v[64:65], v[74:75], v[110:111], v[64:65]
	v_and_b32_e32 v111, 0xffff0000, v128
	v_lshlrev_b32_e32 v110, 16, v128
	v_pk_add_f32 v[64:65], v[64:65], v[110:111]
	v_lshlrev_b32_e32 v112, 16, v132
	v_pk_add_f32 v[64:65], v[64:65], v[112:113]
	s_waitcnt vmcnt(1)
	v_and_b32_e32 v113, 0xffff0000, v136
	v_lshlrev_b32_e32 v112, 16, v136
	v_pk_add_f32 v[64:65], v[64:65], v[112:113]
	s_waitcnt vmcnt(0)
	v_and_b32_e32 v113, 0xffff0000, v140
	v_lshlrev_b32_e32 v112, 16, v140
	v_pk_add_f32 v[64:65], v[64:65], v[112:113]
	v_and_b32_e32 v113, 0xffff0000, v133
	v_pk_fma_f32 v[64:65], v[76:77], v[64:65], v[110:111] neg_lo:[0,0,1] neg_hi:[0,0,1]
	v_pk_fma_f32 v[110:111], v[68:69], v[144:145], 0 op_sel_hi:[1,1,0]
	v_lshlrev_b32_e32 v112, 16, v133
	v_pk_fma_f32 v[66:67], v[70:71], v[66:67], v[110:111]
	v_and_b32_e32 v111, 0xffff0000, v121
	v_lshlrev_b32_e32 v110, 16, v121
	v_pk_fma_f32 v[66:67], v[72:73], v[110:111], v[66:67]
	v_and_b32_e32 v111, 0xffff0000, v125
	v_lshlrev_b32_e32 v110, 16, v125
	v_pk_fma_f32 v[66:67], v[74:75], v[110:111], v[66:67]
	v_and_b32_e32 v111, 0xffff0000, v129
	v_lshlrev_b32_e32 v110, 16, v129
	v_pk_add_f32 v[66:67], v[66:67], v[110:111]
	v_cvt_pk_bf16_f32 v64, v64, v65
	v_pk_add_f32 v[66:67], v[66:67], v[112:113]
	v_and_b32_e32 v113, 0xffff0000, v137
	v_lshlrev_b32_e32 v112, 16, v137
	v_pk_add_f32 v[66:67], v[66:67], v[112:113]
	v_and_b32_e32 v113, 0xffff0000, v141
	v_lshlrev_b32_e32 v112, 16, v141
	v_pk_add_f32 v[66:67], v[66:67], v[112:113]
	v_and_b32_e32 v113, 0xffff0000, v135
	v_pk_fma_f32 v[66:67], v[76:77], v[66:67], v[110:111] neg_lo:[0,0,1] neg_hi:[0,0,1]
	v_and_b32_e32 v111, 0xffff0000, v134
	v_cvt_pk_bf16_f32 v65, v66, v67
	v_pk_fma_f32 v[66:67], v[68:69], v[146:147], 0 op_sel_hi:[1,1,0]
	v_lshlrev_b32_e32 v110, 16, v134
	v_pk_fma_f32 v[66:67], v[70:71], v[108:109], v[66:67]
	v_and_b32_e32 v109, 0xffff0000, v122
	v_lshlrev_b32_e32 v108, 16, v122
	v_pk_fma_f32 v[66:67], v[72:73], v[108:109], v[66:67]
	v_and_b32_e32 v109, 0xffff0000, v126
	v_lshlrev_b32_e32 v108, 16, v126
	v_pk_fma_f32 v[66:67], v[74:75], v[108:109], v[66:67]
	v_and_b32_e32 v109, 0xffff0000, v130
	v_lshlrev_b32_e32 v108, 16, v130
	v_pk_add_f32 v[66:67], v[66:67], v[108:109]
	v_lshlrev_b32_e32 v112, 16, v135
	v_pk_add_f32 v[66:67], v[66:67], v[110:111]
	v_and_b32_e32 v111, 0xffff0000, v138
	v_lshlrev_b32_e32 v110, 16, v138
	v_pk_add_f32 v[66:67], v[66:67], v[110:111]
	v_and_b32_e32 v111, 0xffff0000, v142
	v_lshlrev_b32_e32 v110, 16, v142
	v_pk_add_f32 v[66:67], v[66:67], v[110:111]
	v_and_b32_e32 v111, 0xffff0000, v123
	v_pk_fma_f32 v[66:67], v[76:77], v[66:67], v[108:109] neg_lo:[0,0,1] neg_hi:[0,0,1]
	v_pk_fma_f32 v[108:109], v[68:69], v[148:149], 0 op_sel_hi:[1,1,0]
	v_lshlrev_b32_e32 v110, 16, v123
	v_pk_fma_f32 v[108:109], v[70:71], v[150:151], v[108:109]
	s_mov_b32 s5, 0x11000
	v_pk_fma_f32 v[108:109], v[72:73], v[110:111], v[108:109]
	v_and_b32_e32 v111, 0xffff0000, v127
	v_lshlrev_b32_e32 v110, 16, v127
	v_pk_fma_f32 v[108:109], v[74:75], v[110:111], v[108:109]
	v_and_b32_e32 v111, 0xffff0000, v131
	v_lshlrev_b32_e32 v110, 16, v131
	v_pk_add_f32 v[108:109], v[108:109], v[110:111]
	v_cvt_pk_bf16_f32 v66, v66, v67
	v_pk_add_f32 v[108:109], v[108:109], v[112:113]
	v_and_b32_e32 v113, 0xffff0000, v139
	v_lshlrev_b32_e32 v112, 16, v139
	v_pk_add_f32 v[108:109], v[108:109], v[112:113]
	v_and_b32_e32 v113, 0xffff0000, v143
	v_lshlrev_b32_e32 v112, 16, v143
	v_pk_add_f32 v[108:109], v[108:109], v[112:113]
	s_nop 0
	v_pk_fma_f32 v[108:109], v[76:77], v[108:109], v[110:111] neg_lo:[0,0,1] neg_hi:[0,0,1]
	s_nop 0
	v_cvt_pk_bf16_f32 v67, v108, v109
	v_add_co_u32_e32 v108, vcc, s5, v116
	s_mov_b32 s5, 0x13000
	s_nop 0
	v_addc_co_u32_e32 v109, vcc, 0, v117, vcc
	global_load_dwordx4 v[110:113], v[108:109], off offset:-4096
	s_waitcnt vmcnt(0)
	v_mfma_f32_16x16x32_bf16 v[60:63], v[64:67], v[110:113], v[60:63]
	global_load_dwordx4 v[110:113], v[108:109], off
	s_waitcnt vmcnt(0)
; __device__ __forceinline__ float bf2f(bfr h) { return __uint_as_float(((unsigned)h) << 16); }
; template <int W>
; __device__ __forceinline__ void pool_tile(const Params& p, int row0, int g, int wave, int lane_in) {
;     ...
; #pragma unroll
;     for (int m = 0; m < 2; m++) {
;       int tt = t0 + wave * 32 + m * 16 + fr;
;       int lo = max(tt - W / 2, 0), hi = min(tt + W - W / 2, S);
;       float sum[8];
; #pragma unroll
;       for (int e = 0; e < 8; e++) sum[e] = 0.f;
;       const bfr* colp = xp + (size_t)b * S * 512 + g * 128 + ks * 32 + fq * 8;
;       constexpr int WC = W < 8 ? W : 8;
;       bf16x8 xc = *(const bf16x8*)(colp + (size_t)tt * 512);
; #pragma unroll
;       for (int o0 = 0; o0 < W; o0 += WC) {
;         bf16x8 wv[WC];
; #pragma unroll
;         for (int o = 0; o < WC; o++) {
;           int rc = min(max(tt - W / 2 + o0 + o, 0), S - 1);
;           wv[o] = *(const bf16x8*)(colp + (size_t)rc * 512);
;         }
; #pragma unroll
;         for (int o = 0; o < WC; o++) {
;           int r = tt - W / 2 + o0 + o;
;           float wgt = (r >= 0 && r < S) ? 1.f : 0.f;
; #pragma unroll
;           for (int e = 0; e < 8; e++) sum[e] += wgt * bf2f((bfr)wv[o][e]);
;         }
;         __builtin_amdgcn_sched_barrier(0);
;       }
;       float invn = 1.f / (float)(hi - lo);
;       u32x4 pk;
; #pragma unroll
;       for (int e = 0; e < 4; e++)
;         pk[e] = pack2(sum[2 * e] * invn - bf2f((bfr)xc[2 * e]), sum[2 * e + 1] * invn - bf2f((bfr)xc[2 * e + 1]));
;       bf16x8 af = __builtin_bit_cast(bf16x8, pk);
; #pragma unroll
;       for (int n = 0; n < 8; n++) {
;         bf16x8 bfg = *(const bf16x8*)(wp + (size_t)(n * 16 + fr) * 128 + ks * 32 + fq * 8);
;         acc[m][n] = mfma16(af, bfg, acc[m][n]);
;       }
	v_mfma_f32_16x16x32_bf16 v[52:55], v[64:67], v[110:113], v[52:55]
	v_add_co_u32_e32 v110, vcc, s5, v116
	s_mov_b32 s5, 0x15000
	s_nop 0
	v_addc_co_u32_e32 v111, vcc, 0, v117, vcc
	global_load_dwordx4 v[120:123], v[110:111], off offset:-4096
	v_add_co_u32_e32 v112, vcc, s5, v116
	s_mov_b32 s5, 0x17000
	s_nop 0
	v_addc_co_u32_e32 v113, vcc, 0, v117, vcc
	v_add_co_u32_e32 v116, vcc, s5, v116
	s_waitcnt vmcnt(0)
	v_mfma_f32_16x16x32_bf16 v[44:47], v[64:67], v[120:123], v[44:47]
	global_load_dwordx4 v[120:123], v[110:111], off
	v_addc_co_u32_e32 v117, vcc, 0, v117, vcc
	s_waitcnt vmcnt(0)
	v_mfma_f32_16x16x32_bf16 v[36:39], v[64:67], v[120:123], v[36:39]
	global_load_dwordx4 v[120:123], v[112:113], off offset:-4096
	s_waitcnt vmcnt(0)
	v_mfma_f32_16x16x32_bf16 v[28:31], v[64:67], v[120:123], v[28:31]
	global_load_dwordx4 v[120:123], v[112:113], off
	s_waitcnt vmcnt(0)
	v_mfma_f32_16x16x32_bf16 v[20:23], v[64:67], v[120:123], v[20:23]
	global_load_dwordx4 v[120:123], v[116:117], off offset:-4096
	s_waitcnt vmcnt(0)
	v_mfma_f32_16x16x32_bf16 v[12:15], v[64:67], v[120:123], v[12:15]
	global_load_dwordx4 v[120:123], v[116:117], off
	s_waitcnt vmcnt(0)
	v_mfma_f32_16x16x32_bf16 v[4:7], v[64:67], v[120:123], v[4:7]
	v_add_co_u32_e32 v114, vcc, s90, v114
	v_lshl_add_u64 v[64:65], v[94:95], 0, s[36:37]
	s_nop 0
	v_addc_co_u32_e32 v115, vcc, 0, v115, vcc
	v_lshl_add_u64 v[136:137], v[90:91], 0, s[36:37]
	global_load_dwordx4 v[64:67], v[64:65], off
	s_nop 0
	global_load_dwordx4 v[120:123], v[114:115], off offset:512
	global_load_dwordx4 v[124:127], v[114:115], off offset:1536
	global_load_dwordx4 v[128:131], v[114:115], off offset:2560
	global_load_dwordx4 v[132:135], v[114:115], off offset:3584
	s_nop 0
	global_load_dwordx4 v[136:139], v[136:137], off
	v_lshl_add_u64 v[114:115], v[88:89], 0, s[36:37]
	v_lshl_add_u64 v[144:145], v[86:87], 0, s[36:37]
	global_load_dwordx4 v[140:143], v[114:115], off
	s_nop 0
	global_load_dwordx4 v[144:147], v[144:145], off
	s_waitcnt vmcnt(6)
	v_and_b32_e32 v115, 0xffff0000, v120
	v_lshlrev_b32_e32 v114, 16, v120
	v_and_b32_e32 v149, 0xffff0000, v121
	v_lshlrev_b32_e32 v148, 16, v121
	v_and_b32_e32 v121, 0xffff0000, v122
	v_lshlrev_b32_e32 v120, 16, v122
	v_and_b32_e32 v151, 0xffff0000, v123
	v_lshlrev_b32_e32 v150, 16, v123
	v_pk_add_f32 v[114:115], v[114:115], 0 op_sel_hi:[1,0]
	s_waitcnt vmcnt(5)
	v_and_b32_e32 v123, 0xffff0000, v124
	v_lshlrev_b32_e32 v122, 16, v124
	v_pk_add_f32 v[114:115], v[114:115], v[122:123]
	s_waitcnt vmcnt(4)
	v_and_b32_e32 v123, 0xffff0000, v128
	v_lshlrev_b32_e32 v122, 16, v128
	v_pk_add_f32 v[114:115], v[114:115], v[122:123]
	s_waitcnt vmcnt(3)
	v_and_b32_e32 v123, 0xffff0000, v132
	v_lshlrev_b32_e32 v122, 16, v132
	v_pk_add_f32 v[114:115], v[114:115], v[122:123]
	v_and_b32_e32 v123, 0xffff0000, v64
	v_lshlrev_b32_e32 v122, 16, v64
	v_pk_add_f32 v[114:115], v[114:115], v[122:123]
	s_waitcnt vmcnt(2)
	v_and_b32_e32 v153, 0xffff0000, v136
	v_lshlrev_b32_e32 v152, 16, v136
	v_pk_fma_f32 v[114:115], v[78:79], v[152:153], v[114:115]
	s_waitcnt vmcnt(1)
	v_and_b32_e32 v153, 0xffff0000, v140
	v_lshlrev_b32_e32 v152, 16, v140
	v_pk_fma_f32 v[114:115], v[80:81], v[152:153], v[114:115]
	s_waitcnt vmcnt(0)
	v_and_b32_e32 v153, 0xffff0000, v144
	v_lshlrev_b32_e32 v152, 16, v144
	v_pk_fma_f32 v[114:115], v[82:83], v[152:153], v[114:115]
	v_lshlrev_b32_e32 v124, 16, v137
	v_pk_fma_f32 v[114:115], v[84:85], v[114:115], v[122:123] neg_lo:[0,0,1] neg_hi:[0,0,1]
	v_and_b32_e32 v123, 0xffff0000, v125
	v_cvt_pk_bf16_f32 v64, v114, v115
	v_pk_add_f32 v[114:115], v[148:149], 0 op_sel_hi:[1,0]
	v_lshlrev_b32_e32 v122, 16, v125
	v_pk_add_f32 v[114:115], v[114:115], v[122:123]
	v_and_b32_e32 v123, 0xffff0000, v129
	v_lshlrev_b32_e32 v122, 16, v129
	v_pk_add_f32 v[114:115], v[114:115], v[122:123]
	v_and_b32_e32 v123, 0xffff0000, v133
	v_lshlrev_b32_e32 v122, 16, v133
	v_pk_add_f32 v[114:115], v[114:115], v[122:123]
	v_and_b32_e32 v123, 0xffff0000, v65
	v_lshlrev_b32_e32 v122, 16, v65
	v_pk_add_f32 v[114:115], v[114:115], v[122:123]
	v_and_b32_e32 v125, 0xffff0000, v137
	v_pk_fma_f32 v[114:115], v[78:79], v[124:125], v[114:115]
	v_and_b32_e32 v125, 0xffff0000, v141
	v_lshlrev_b32_e32 v124, 16, v141
	v_pk_fma_f32 v[114:115], v[80:81], v[124:125], v[114:115]
	v_and_b32_e32 v125, 0xffff0000, v145
	v_lshlrev_b32_e32 v124, 16, v145
	v_pk_fma_f32 v[114:115], v[82:83], v[124:125], v[114:115]
	s_nop 0
	v_pk_fma_f32 v[114:115], v[84:85], v[114:115], v[122:123] neg_lo:[0,0,1] neg_hi:[0,0,1]
	v_and_b32_e32 v123, 0xffff0000, v138
	v_cvt_pk_bf16_f32 v65, v114, v115
	v_pk_add_f32 v[114:115], v[120:121], 0 op_sel_hi:[1,0]
	v_and_b32_e32 v121, 0xffff0000, v126
	v_lshlrev_b32_e32 v120, 16, v126
	v_pk_add_f32 v[114:115], v[114:115], v[120:121]
	v_and_b32_e32 v121, 0xffff0000, v130
	v_lshlrev_b32_e32 v120, 16, v130
	v_pk_add_f32 v[114:115], v[114:115], v[120:121]
	v_and_b32_e32 v121, 0xffff0000, v134
	v_lshlrev_b32_e32 v120, 16, v134
	v_pk_add_f32 v[114:115], v[114:115], v[120:121]
	v_and_b32_e32 v121, 0xffff0000, v66
	v_lshlrev_b32_e32 v120, 16, v66
	v_pk_add_f32 v[114:115], v[114:115], v[120:121]
	v_lshlrev_b32_e32 v122, 16, v138
	v_pk_fma_f32 v[114:115], v[78:79], v[122:123], v[114:115]
	v_and_b32_e32 v123, 0xffff0000, v142
	v_lshlrev_b32_e32 v122, 16, v142
	v_pk_fma_f32 v[114:115], v[80:81], v[122:123], v[114:115]
	v_and_b32_e32 v123, 0xffff0000, v146
	v_lshlrev_b32_e32 v122, 16, v146
	v_pk_fma_f32 v[114:115], v[82:83], v[122:123], v[114:115]
	v_and_b32_e32 v123, 0xffff0000, v139
	v_pk_fma_f32 v[114:115], v[84:85], v[114:115], v[120:121] neg_lo:[0,0,1] neg_hi:[0,0,1]
	v_and_b32_e32 v121, 0xffff0000, v127
	v_cvt_pk_bf16_f32 v66, v114, v115
	v_pk_add_f32 v[114:115], v[150:151], 0 op_sel_hi:[1,0]
	v_lshlrev_b32_e32 v120, 16, v127
	v_pk_add_f32 v[114:115], v[114:115], v[120:121]
	v_and_b32_e32 v121, 0xffff0000, v131
	v_lshlrev_b32_e32 v120, 16, v131
	v_pk_add_f32 v[114:115], v[114:115], v[120:121]
	v_and_b32_e32 v121, 0xffff0000, v135
	v_lshlrev_b32_e32 v120, 16, v135
	v_pk_add_f32 v[114:115], v[114:115], v[120:121]
	v_and_b32_e32 v121, 0xffff0000, v67
	v_lshlrev_b32_e32 v120, 16, v67
	v_pk_add_f32 v[114:115], v[114:115], v[120:121]
	v_lshlrev_b32_e32 v122, 16, v139
	v_pk_fma_f32 v[114:115], v[78:79], v[122:123], v[114:115]
	v_and_b32_e32 v123, 0xffff0000, v143
	v_lshlrev_b32_e32 v122, 16, v143
	v_pk_fma_f32 v[114:115], v[80:81], v[122:123], v[114:115]
	v_and_b32_e32 v123, 0xffff0000, v147
	v_lshlrev_b32_e32 v122, 16, v147
	v_pk_fma_f32 v[114:115], v[82:83], v[122:123], v[114:115]
	s_nop 0
	v_pk_fma_f32 v[114:115], v[84:85], v[114:115], v[120:121] neg_lo:[0,0,1] neg_hi:[0,0,1]
	global_load_dwordx4 v[120:123], v[108:109], off offset:-4096
	v_cvt_pk_bf16_f32 v67, v114, v115
	s_waitcnt vmcnt(0)
; template <int W>
; __device__ __forceinline__ void pool_tile(const Params& p, int row0, int g, int wave, int lane_in) {
;     ...
; #pragma unroll
;       for (int n = 0; n < 8; n++) {
;         bf16x8 bfg = *(const bf16x8*)(wp + (size_t)(n * 16 + fr) * 128 + ks * 32 + fq * 8);
;         acc[m][n] = mfma16(af, bfg, acc[m][n]);
;       }
;       __builtin_amdgcn_sched_barrier(0);
;     }
;   }
; #pragma unroll
;   for (int n = 0; n < 8; n++) {
;     float cs = p.c_scale[g * 128 + n * 16 + fr];
; #pragma unroll
;     for (int m = 0; m < 2; m++)
; #pragma unroll
;       for (int j = 0; j < 4; j++) {
;         size_t row = (size_t)row0 + wave * 32 + m * 16 + fq * 4 + j;
;         p.mix[row * D + g * 128 + n * 16 + fr] = f2bf(acc[m][n][j] * cs);
;       }
;   }
	s_nop 0
	v_mfma_f32_16x16x32_bf16 v[56:59], v[64:67], v[120:123], v[56:59]
	global_load_dwordx4 v[216:219], v[108:109], off
	global_load_dwordx4 v[220:223], v[110:111], off offset:-4096
	s_nop 0
	global_load_dwordx4 v[224:227], v[110:111], off
	global_load_dwordx4 v[228:231], v[112:113], off offset:-4096
	global_load_dwordx4 v[232:235], v[112:113], off
	global_load_dwordx4 v[236:239], v[116:117], off offset:-4096
	global_load_dwordx4 v[240:243], v[116:117], off
	s_waitcnt vmcnt(6)
	v_mfma_f32_16x16x32_bf16 v[48:51], v[64:67], v[216:219], v[48:51]
	s_waitcnt vmcnt(4)
	v_mfma_f32_16x16x32_bf16 v[32:35], v[64:67], v[224:227], v[32:35]
	v_mfma_f32_16x16x32_bf16 v[40:43], v[64:67], v[220:223], v[40:43]
	s_waitcnt vmcnt(3)
	v_mfma_f32_16x16x32_bf16 v[24:27], v[64:67], v[228:231], v[24:27]
	s_waitcnt vmcnt(2)
	v_mfma_f32_16x16x32_bf16 v[16:19], v[64:67], v[232:235], v[16:19]
	s_waitcnt vmcnt(1)
	v_mfma_f32_16x16x32_bf16 v[8:11], v[64:67], v[236:239], v[8:11]
	s_waitcnt vmcnt(0)
	v_mfma_f32_16x16x32_bf16 v[0:3], v[64:67], v[240:243], v[0:3]
	s_add_u32 s36, s36, 64
	s_addc_u32 s37, s37, 0
	s_cmpk_lg_i32 s36, 0x100
	s_cbranch_scc1 .LBB0_1159
	s_ashr_i32 s55, s54, 31
	v_lshlrev_b32_e32 v64, 2, v119
	v_readlane_b32 s60, v255, 10
	s_or_b64 s[36:37], s[54:55], s[0:1]
	v_ashrrev_i32_e32 v65, 31, v64
	v_lshlrev_b32_e32 v92, 1, v118
	v_readlane_b32 s61, v255, 11
	v_readlane_b32 s62, v255, 12
	v_readlane_b32 s63, v255, 13
	v_readlane_b32 s64, v255, 14
	v_readlane_b32 s65, v255, 15
	v_readlane_b32 s66, v255, 16
	v_readlane_b32 s67, v255, 17
	v_readlane_b32 s68, v255, 18
	v_readlane_b32 s69, v255, 19
	v_readlane_b32 s70, v255, 20
	v_readlane_b32 s71, v255, 21
	v_readlane_b32 s72, v255, 22
	v_readlane_b32 s73, v255, 23
	v_readlane_b32 s74, v255, 24
	v_readlane_b32 s75, v255, 25
	v_lshl_add_u64 v[66:67], s[36:37], 0, v[64:65]
	v_lshl_add_u64 v[64:65], s[68:69], 0, v[92:93]
	v_readlane_b32 s60, v254, 38
	v_lshlrev_b32_e32 v72, 2, v118
	v_readlane_b32 s68, v254, 46
	v_readlane_b32 s69, v254, 47
	v_lshlrev_b64 v[74:75], 11, v[66:67]
	v_lshl_add_u64 v[66:67], v[64:65], 0, v[74:75]
	v_readlane_b32 s61, v254, 39
	v_readlane_b32 s62, v254, 40
	v_readlane_b32 s63, v254, 41
	global_load_dword v73, v72, s[68:69] offset:1024
	v_readlane_b32 s64, v254, 42
	v_readlane_b32 s65, v254, 43
	v_readlane_b32 s66, v254, 44
	v_readlane_b32 s67, v254, 45
	v_readlane_b32 s70, v254, 48
	v_readlane_b32 s71, v254, 49
	v_readlane_b32 s72, v254, 50
	v_readlane_b32 s73, v254, 51
	v_readlane_b32 s74, v254, 52
	v_readlane_b32 s75, v254, 53
	s_waitcnt vmcnt(0)
	v_mul_f32_e32 v60, v60, v73
	v_cvt_pk_bf16_f32 v60, v60, s0
	global_store_short v[66:67], v60, off offset:512
	v_mul_f32_e32 v60, v61, v73
	v_cvt_pk_bf16_f32 v60, v60, s0
	global_store_short v[66:67], v60, off offset:2560
	v_mul_f32_e32 v60, v62, v73
	v_cvt_pk_bf16_f32 v62, v60, s0
	v_or_b32_e32 v60, 0x1000, v74
	v_mov_b32_e32 v61, v75
	v_lshl_add_u64 v[68:69], v[64:65], 0, v[60:61]
	global_store_short v[68:69], v62, off offset:512
	v_mul_f32_e32 v62, v63, v73
	v_cvt_pk_bf16_f32 v70, v62, s0
	v_or_b32_e32 v62, 0x1800, v74
	v_mov_b32_e32 v63, v75
	v_lshl_add_u64 v[68:69], v[64:65], 0, v[62:63]
	global_store_short v[68:69], v70, off offset:512
	v_mul_f32_e32 v56, v56, v73
	v_add_co_u32_e32 v70, vcc, s91, v66
	v_cvt_pk_bf16_f32 v56, v56, s0
	s_nop 0
	v_addc_co_u32_e32 v71, vcc, 0, v67, vcc
	global_store_short v[70:71], v56, off offset:512
	v_mul_f32_e32 v56, v57, v73
	v_cvt_pk_bf16_f32 v76, v56, s0
	global_store_short v[70:71], v76, off offset:2560
	v_mul_f32_e32 v58, v58, v73
	v_add_co_u32_e32 v76, vcc, s92, v66
	v_cvt_pk_bf16_f32 v58, v58, s0
	s_nop 0
	v_addc_co_u32_e32 v77, vcc, 0, v67, vcc
	global_store_short v[76:77], v58, off offset:512
	v_mul_f32_e32 v58, v59, v73
	v_cvt_pk_bf16_f32 v73, v58, s0
	global_store_short v[76:77], v73, off offset:2560
	global_load_dword v73, v72, s[68:69] offset:1088
	v_lshl_add_u64 v[68:69], v[74:75], 0, s[30:31]
	v_lshl_add_u64 v[56:57], v[74:75], 0, s[34:35]
	v_lshl_add_u64 v[70:71], v[74:75], 0, s[38:39]
	v_lshl_add_u64 v[58:59], v[74:75], 0, s[40:41]
	v_lshl_add_u64 v[74:75], v[64:65], 0, 32
	s_waitcnt vmcnt(0)
	v_mul_f32_e32 v52, v52, v73
	v_cvt_pk_bf16_f32 v52, v52, s0
	global_store_short v[66:67], v52, off offset:544
	v_mul_f32_e32 v52, v53, v73
	v_cvt_pk_bf16_f32 v52, v52, s0
	global_store_short v[66:67], v52, off offset:2592
	v_mul_f32_e32 v52, v54, v73
	v_cvt_pk_bf16_f32 v54, v52, s0
	v_lshl_add_u64 v[52:53], v[74:75], 0, v[60:61]
	global_store_short v[52:53], v54, off offset:512
	v_mul_f32_e32 v52, v55, v73
	v_cvt_pk_bf16_f32 v54, v52, s0
	v_lshl_add_u64 v[52:53], v[74:75], 0, v[62:63]
	v_mul_f32_e32 v48, v48, v73
	global_store_short v[52:53], v54, off offset:512
	v_cvt_pk_bf16_f32 v48, v48, s0
	v_lshl_add_u64 v[52:53], v[74:75], 0, v[68:69]
	global_store_short v[52:53], v48, off offset:512
	v_mul_f32_e32 v48, v49, v73
	v_cvt_pk_bf16_f32 v52, v48, s0
	v_lshl_add_u64 v[48:49], v[74:75], 0, v[56:57]
	global_store_short v[48:49], v52, off offset:512
	v_mul_f32_e32 v48, v50, v73
	v_cvt_pk_bf16_f32 v50, v48, s0
	v_lshl_add_u64 v[48:49], v[74:75], 0, v[70:71]
	global_store_short v[48:49], v50, off offset:512
	v_mul_f32_e32 v48, v51, v73
	v_cvt_pk_bf16_f32 v50, v48, s0
	v_lshl_add_u64 v[48:49], v[74:75], 0, v[58:59]
	global_store_short v[48:49], v50, off offset:512
	global_load_dword v50, v72, s[68:69] offset:1152
	v_lshl_add_u64 v[48:49], v[64:65], 0, 64
	s_waitcnt vmcnt(0)
; template <int W>
; __device__ __forceinline__ void pool_tile(const Params& p, int row0, int g, int wave, int lane_in) {
;     ...
; #pragma unroll
;   for (int n = 0; n < 8; n++) {
;     float cs = p.c_scale[g * 128 + n * 16 + fr];
; #pragma unroll
;     for (int m = 0; m < 2; m++)
; #pragma unroll
;       for (int j = 0; j < 4; j++) {
;         size_t row = (size_t)row0 + wave * 32 + m * 16 + fq * 4 + j;
;         p.mix[row * D + g * 128 + n * 16 + fr] = f2bf(acc[m][n][j] * cs);
;       }
;   }
	v_mul_f32_e32 v44, v44, v50
	v_cvt_pk_bf16_f32 v44, v44, s0
	global_store_short v[66:67], v44, off offset:576
	v_mul_f32_e32 v44, v45, v50
	v_cvt_pk_bf16_f32 v44, v44, s0
	global_store_short v[66:67], v44, off offset:2624
	v_mul_f32_e32 v44, v46, v50
	v_cvt_pk_bf16_f32 v46, v44, s0
	v_lshl_add_u64 v[44:45], v[48:49], 0, v[60:61]
	global_store_short v[44:45], v46, off offset:512
	v_mul_f32_e32 v44, v47, v50
	v_cvt_pk_bf16_f32 v46, v44, s0
	v_lshl_add_u64 v[44:45], v[48:49], 0, v[62:63]
	v_mul_f32_e32 v40, v40, v50
	global_store_short v[44:45], v46, off offset:512
	v_cvt_pk_bf16_f32 v40, v40, s0
	v_lshl_add_u64 v[44:45], v[48:49], 0, v[68:69]
	global_store_short v[44:45], v40, off offset:512
	v_mul_f32_e32 v40, v41, v50
	v_cvt_pk_bf16_f32 v44, v40, s0
	v_lshl_add_u64 v[40:41], v[48:49], 0, v[56:57]
	global_store_short v[40:41], v44, off offset:512
	v_mul_f32_e32 v40, v42, v50
	v_cvt_pk_bf16_f32 v42, v40, s0
	v_lshl_add_u64 v[40:41], v[48:49], 0, v[70:71]
	global_store_short v[40:41], v42, off offset:512
	v_mul_f32_e32 v40, v43, v50
	v_cvt_pk_bf16_f32 v42, v40, s0
	v_lshl_add_u64 v[40:41], v[48:49], 0, v[58:59]
	global_store_short v[40:41], v42, off offset:512
	global_load_dword v42, v72, s[68:69] offset:1216
	v_lshl_add_u64 v[40:41], v[64:65], 0, s[42:43]
	s_waitcnt vmcnt(0)
	v_mul_f32_e32 v36, v36, v42
	v_cvt_pk_bf16_f32 v36, v36, s0
	global_store_short v[66:67], v36, off offset:608
	v_mul_f32_e32 v36, v37, v42
	v_cvt_pk_bf16_f32 v36, v36, s0
	global_store_short v[66:67], v36, off offset:2656
	v_mul_f32_e32 v36, v38, v42
	v_cvt_pk_bf16_f32 v38, v36, s0
	v_lshl_add_u64 v[36:37], v[40:41], 0, v[60:61]
	global_store_short v[36:37], v38, off offset:512
	v_mul_f32_e32 v36, v39, v42
	v_cvt_pk_bf16_f32 v38, v36, s0
	v_lshl_add_u64 v[36:37], v[40:41], 0, v[62:63]
	v_mul_f32_e32 v32, v32, v42
	global_store_short v[36:37], v38, off offset:512
	v_cvt_pk_bf16_f32 v32, v32, s0
	v_lshl_add_u64 v[36:37], v[40:41], 0, v[68:69]
	global_store_short v[36:37], v32, off offset:512
	v_mul_f32_e32 v32, v33, v42
	v_cvt_pk_bf16_f32 v36, v32, s0
	v_lshl_add_u64 v[32:33], v[40:41], 0, v[56:57]
	global_store_short v[32:33], v36, off offset:512
	v_mul_f32_e32 v32, v34, v42
	v_cvt_pk_bf16_f32 v34, v32, s0
	v_lshl_add_u64 v[32:33], v[40:41], 0, v[70:71]
	global_store_short v[32:33], v34, off offset:512
	v_mul_f32_e32 v32, v35, v42
	v_cvt_pk_bf16_f32 v34, v32, s0
	v_lshl_add_u64 v[32:33], v[40:41], 0, v[58:59]
	global_store_short v[32:33], v34, off offset:512
	global_load_dword v34, v72, s[68:69] offset:1280
	v_lshl_add_u64 v[32:33], v[64:65], 0, s[44:45]
	s_waitcnt vmcnt(0)
	v_mul_f32_e32 v28, v28, v34
	v_cvt_pk_bf16_f32 v28, v28, s0
	global_store_short v[66:67], v28, off offset:640
	v_mul_f32_e32 v28, v29, v34
	v_cvt_pk_bf16_f32 v28, v28, s0
	global_store_short v[66:67], v28, off offset:2688
	v_mul_f32_e32 v28, v30, v34
	v_cvt_pk_bf16_f32 v30, v28, s0
	v_lshl_add_u64 v[28:29], v[32:33], 0, v[60:61]
	global_store_short v[28:29], v30, off offset:512
	v_mul_f32_e32 v28, v31, v34
	v_cvt_pk_bf16_f32 v30, v28, s0
	v_lshl_add_u64 v[28:29], v[32:33], 0, v[62:63]
	v_mul_f32_e32 v24, v24, v34
	global_store_short v[28:29], v30, off offset:512
	v_cvt_pk_bf16_f32 v24, v24, s0
	v_lshl_add_u64 v[28:29], v[32:33], 0, v[68:69]
	global_store_short v[28:29], v24, off offset:512
	v_mul_f32_e32 v24, v25, v34
	v_cvt_pk_bf16_f32 v28, v24, s0
	v_lshl_add_u64 v[24:25], v[32:33], 0, v[56:57]
	global_store_short v[24:25], v28, off offset:512
	v_mul_f32_e32 v24, v26, v34
	v_cvt_pk_bf16_f32 v26, v24, s0
	v_lshl_add_u64 v[24:25], v[32:33], 0, v[70:71]
	global_store_short v[24:25], v26, off offset:512
	v_mul_f32_e32 v24, v27, v34
	v_cvt_pk_bf16_f32 v26, v24, s0
	v_lshl_add_u64 v[24:25], v[32:33], 0, v[58:59]
	global_store_short v[24:25], v26, off offset:512
	global_load_dword v26, v72, s[68:69] offset:1344
	v_lshl_add_u64 v[24:25], v[64:65], 0, s[46:47]
	s_waitcnt vmcnt(0)
; template <int W>
; __device__ __forceinline__ void pool_tile(const Params& p, int row0, int g, int wave, int lane_in) {
;     ...
; #pragma unroll
;   for (int n = 0; n < 8; n++) {
;     float cs = p.c_scale[g * 128 + n * 16 + fr];
; #pragma unroll
;     for (int m = 0; m < 2; m++)
; #pragma unroll
;       for (int j = 0; j < 4; j++) {
;         size_t row = (size_t)row0 + wave * 32 + m * 16 + fq * 4 + j;
;         p.mix[row * D + g * 128 + n * 16 + fr] = f2bf(acc[m][n][j] * cs);
;       }
;   }
	v_mul_f32_e32 v20, v20, v26
	v_cvt_pk_bf16_f32 v20, v20, s0
	global_store_short v[66:67], v20, off offset:672
	v_mul_f32_e32 v20, v21, v26
	v_cvt_pk_bf16_f32 v20, v20, s0
	global_store_short v[66:67], v20, off offset:2720
	v_mul_f32_e32 v20, v22, v26
	v_cvt_pk_bf16_f32 v22, v20, s0
	v_lshl_add_u64 v[20:21], v[24:25], 0, v[60:61]
	global_store_short v[20:21], v22, off offset:512
	v_mul_f32_e32 v20, v23, v26
	v_cvt_pk_bf16_f32 v22, v20, s0
	v_lshl_add_u64 v[20:21], v[24:25], 0, v[62:63]
	v_mul_f32_e32 v16, v16, v26
	global_store_short v[20:21], v22, off offset:512
	v_cvt_pk_bf16_f32 v16, v16, s0
	v_lshl_add_u64 v[20:21], v[24:25], 0, v[68:69]
	global_store_short v[20:21], v16, off offset:512
	v_mul_f32_e32 v16, v17, v26
	v_cvt_pk_bf16_f32 v20, v16, s0
	v_lshl_add_u64 v[16:17], v[24:25], 0, v[56:57]
	global_store_short v[16:17], v20, off offset:512
	v_mul_f32_e32 v16, v18, v26
	v_cvt_pk_bf16_f32 v18, v16, s0
	v_lshl_add_u64 v[16:17], v[24:25], 0, v[70:71]
	global_store_short v[16:17], v18, off offset:512
	v_mul_f32_e32 v16, v19, v26
	v_cvt_pk_bf16_f32 v18, v16, s0
	v_lshl_add_u64 v[16:17], v[24:25], 0, v[58:59]
	global_store_short v[16:17], v18, off offset:512
	global_load_dword v18, v72, s[68:69] offset:1408
	v_lshl_add_u64 v[16:17], v[64:65], 0, s[48:49]
	s_waitcnt vmcnt(0)
	v_mul_f32_e32 v12, v12, v18
	v_cvt_pk_bf16_f32 v12, v12, s0
	global_store_short v[66:67], v12, off offset:704
	v_mul_f32_e32 v12, v13, v18
	v_cvt_pk_bf16_f32 v12, v12, s0
	global_store_short v[66:67], v12, off offset:2752
	v_mul_f32_e32 v12, v14, v18
	v_cvt_pk_bf16_f32 v14, v12, s0
	v_lshl_add_u64 v[12:13], v[16:17], 0, v[60:61]
	global_store_short v[12:13], v14, off offset:512
	v_mul_f32_e32 v12, v15, v18
	v_cvt_pk_bf16_f32 v14, v12, s0
	v_lshl_add_u64 v[12:13], v[16:17], 0, v[62:63]
	v_mul_f32_e32 v8, v8, v18
	global_store_short v[12:13], v14, off offset:512
	v_cvt_pk_bf16_f32 v8, v8, s0
	v_lshl_add_u64 v[12:13], v[16:17], 0, v[68:69]
	global_store_short v[12:13], v8, off offset:512
	v_mul_f32_e32 v8, v9, v18
	v_cvt_pk_bf16_f32 v12, v8, s0
	v_lshl_add_u64 v[8:9], v[16:17], 0, v[56:57]
	global_store_short v[8:9], v12, off offset:512
	v_mul_f32_e32 v8, v10, v18
	v_cvt_pk_bf16_f32 v10, v8, s0
	v_lshl_add_u64 v[8:9], v[16:17], 0, v[70:71]
	global_store_short v[8:9], v10, off offset:512
	v_mul_f32_e32 v8, v11, v18
	v_cvt_pk_bf16_f32 v10, v8, s0
	v_lshl_add_u64 v[8:9], v[16:17], 0, v[58:59]
	global_store_short v[8:9], v10, off offset:512
	global_load_dword v8, v72, s[68:69] offset:1472
	v_lshl_add_u64 v[10:11], v[64:65], 0, s[50:51]
	s_waitcnt vmcnt(0)
	v_mul_f32_e32 v4, v4, v8
	v_cvt_pk_bf16_f32 v4, v4, s0
	global_store_short v[66:67], v4, off offset:736
	v_mul_f32_e32 v4, v5, v8
	v_cvt_pk_bf16_f32 v4, v4, s0
	global_store_short v[66:67], v4, off offset:2784
	v_mul_f32_e32 v4, v6, v8
	v_cvt_pk_bf16_f32 v6, v4, s0
	v_lshl_add_u64 v[4:5], v[10:11], 0, v[60:61]
	global_store_short v[4:5], v6, off offset:512
	v_mul_f32_e32 v4, v7, v8
	v_cvt_pk_bf16_f32 v6, v4, s0
	v_lshl_add_u64 v[4:5], v[10:11], 0, v[62:63]
	v_mul_f32_e32 v0, v0, v8
	global_store_short v[4:5], v6, off offset:512
	v_cvt_pk_bf16_f32 v0, v0, s0
	v_lshl_add_u64 v[4:5], v[10:11], 0, v[68:69]
	global_store_short v[4:5], v0, off offset:512
	v_mul_f32_e32 v0, v1, v8
	v_cvt_pk_bf16_f32 v4, v0, s0
	v_lshl_add_u64 v[0:1], v[10:11], 0, v[56:57]
	global_store_short v[0:1], v4, off offset:512
	v_mul_f32_e32 v0, v2, v8
	v_cvt_pk_bf16_f32 v2, v0, s0
	v_lshl_add_u64 v[0:1], v[10:11], 0, v[70:71]
	global_store_short v[0:1], v2, off offset:512
	v_mul_f32_e32 v0, v3, v8
	v_cvt_pk_bf16_f32 v2, v0, s0
	v_lshl_add_u64 v[0:1], v[10:11], 0, v[58:59]
	global_store_short v[0:1], v2, off offset:512

; __device__ __forceinline__ float bf2f(bfr h) { return __uint_as_float(((unsigned)h) << 16); }
; template <int W>
; __device__ __forceinline__ void pool_tile(const Params& p, int row0, int g, int wave, int lane_in) {
;     ...
;   for (int ks = 0; ks < 4; ks++) {
; #pragma unroll
;     for (int m = 0; m < 2; m++) {
;       int tt = t0 + wave * 32 + m * 16 + fr;
;       int lo = max(tt - W / 2, 0), hi = min(tt + W - W / 2, S);
;       float sum[8];
; #pragma unroll
;       for (int e = 0; e < 8; e++) sum[e] = 0.f;
;       const bfr* colp = xp + (size_t)b * S * 512 + g * 128 + ks * 32 + fq * 8;
;       constexpr int WC = W < 8 ? W : 8;
;       bf16x8 xc = *(const bf16x8*)(colp + (size_t)tt * 512);
; #pragma unroll
;       for (int o0 = 0; o0 < W; o0 += WC) {
;         bf16x8 wv[WC];
; #pragma unroll
;         for (int o = 0; o < WC; o++) {
;           int rc = min(max(tt - W / 2 + o0 + o, 0), S - 1);
;           wv[o] = *(const bf16x8*)(colp + (size_t)rc * 512);
;         }
; #pragma unroll
;         for (int o = 0; o < WC; o++) {
;           int r = tt - W / 2 + o0 + o;
;           float wgt = (r >= 0 && r < S) ? 1.f : 0.f;
; #pragma unroll
;           for (int e = 0; e < 8; e++) sum[e] += wgt * bf2f((bfr)wv[o][e]);
;         }
;         __builtin_amdgcn_sched_barrier(0);
;       }
;       float invn = 1.f / (float)(hi - lo);
;       u32x4 pk;
; #pragma unroll
;       for (int e = 0; e < 4; e++)
;         pk[e] = pack2(sum[2 * e] * invn - bf2f((bfr)xc[2 * e]), sum[2 * e + 1] * invn - bf2f((bfr)xc[2 * e + 1]));
;       bf16x8 af = __builtin_bit_cast(bf16x8, pk);
; #pragma unroll
;       for (int n = 0; n < 8; n++) {
;         bf16x8 bfg = *(const bf16x8*)(wp + (size_t)(n * 16 + fr) * 128 + ks * 32 + fq * 8);
;         acc[m][n] = mfma16(af, bfg, acc[m][n]);
;       }
;       __builtin_amdgcn_sched_barrier(0);
;     }
.LBB0_1165:
	v_lshl_add_u64 v[82:83], v[74:75], 0, s[36:37]
	v_lshl_add_u64 v[78:79], v[76:77], 0, s[36:37]
	global_load_dwordx4 v[64:67], v[82:83], off
	global_load_dwordx4 v[84:87], v[78:79], off
	v_lshl_add_u64 v[78:79], v[72:73], 0, s[36:37]
	s_waitcnt vmcnt(0)
	v_and_b32_e32 v81, 0xffff0000, v84
	v_lshlrev_b32_e32 v80, 16, v84
	v_pk_fma_f32 v[80:81], v[68:69], v[80:81], 0 op_sel_hi:[1,1,0]
	v_and_b32_e32 v89, 0xffff0000, v64
	v_lshlrev_b32_e32 v88, 16, v64
	v_pk_add_f32 v[80:81], v[80:81], v[88:89]
	v_lshlrev_b32_e32 v84, 16, v65
	v_pk_fma_f32 v[80:81], v[70:71], v[80:81], v[88:89] neg_lo:[0,0,1] neg_hi:[0,0,1]
	s_movk_i32 s4, 0x6000
	v_cvt_pk_bf16_f32 v64, v80, v81
	v_and_b32_e32 v81, 0xffff0000, v85
	v_lshlrev_b32_e32 v80, 16, v85
	v_pk_fma_f32 v[80:81], v[68:69], v[80:81], 0 op_sel_hi:[1,1,0]
	v_and_b32_e32 v85, 0xffff0000, v65
	v_pk_add_f32 v[80:81], v[80:81], v[84:85]
	s_nop 0
	v_pk_fma_f32 v[80:81], v[70:71], v[80:81], v[84:85] neg_lo:[0,0,1] neg_hi:[0,0,1]
	v_and_b32_e32 v85, 0xffff0000, v66
	v_cvt_pk_bf16_f32 v65, v80, v81
	v_and_b32_e32 v81, 0xffff0000, v86
	v_lshlrev_b32_e32 v80, 16, v86
	v_pk_fma_f32 v[80:81], v[68:69], v[80:81], 0 op_sel_hi:[1,1,0]
	v_lshlrev_b32_e32 v84, 16, v66
	v_pk_add_f32 v[80:81], v[80:81], v[84:85]
	s_nop 0
	v_pk_fma_f32 v[80:81], v[70:71], v[80:81], v[84:85] neg_lo:[0,0,1] neg_hi:[0,0,1]
	v_and_b32_e32 v85, 0xffff0000, v67
	v_cvt_pk_bf16_f32 v66, v80, v81
	v_and_b32_e32 v81, 0xffff0000, v87
	v_lshlrev_b32_e32 v80, 16, v87
	v_pk_fma_f32 v[80:81], v[68:69], v[80:81], 0 op_sel_hi:[1,1,0]
	v_lshlrev_b32_e32 v84, 16, v67
	v_pk_add_f32 v[80:81], v[80:81], v[84:85]
	s_nop 0
	v_pk_fma_f32 v[80:81], v[70:71], v[80:81], v[84:85] neg_lo:[0,0,1] neg_hi:[0,0,1]
	global_load_dwordx4 v[84:87], v[78:79], off
	v_cvt_pk_bf16_f32 v67, v80, v81
	v_add_co_u32_e32 v80, vcc, s87, v78
	s_waitcnt vmcnt(0)
	v_mfma_f32_16x16x32_bf16 v[60:63], v[64:67], v[84:87], v[60:63]
	v_addc_co_u32_e32 v81, vcc, 0, v79, vcc
	global_load_dwordx4 v[84:87], v[80:81], off offset:-4096
	s_waitcnt vmcnt(0)
	v_mfma_f32_16x16x32_bf16 v[52:55], v[64:67], v[84:87], v[52:55]
	global_load_dwordx4 v[84:87], v[80:81], off
	s_waitcnt vmcnt(0)
	v_mfma_f32_16x16x32_bf16 v[44:47], v[64:67], v[84:87], v[44:47]
	v_add_co_u32_e32 v86, vcc, s2, v78
	s_nop 1
	v_addc_co_u32_e32 v87, vcc, 0, v79, vcc
	global_load_dwordx4 v[94:97], v[86:87], off offset:-4096
	v_add_co_u32_e32 v88, vcc, s4, v78
	s_movk_i32 s4, 0x7000
	s_nop 0
	v_addc_co_u32_e32 v89, vcc, 0, v79, vcc
	v_add_co_u32_e32 v84, vcc, s4, v78
	s_waitcnt vmcnt(0)
	v_mfma_f32_16x16x32_bf16 v[36:39], v[64:67], v[94:97], v[36:39]
	global_load_dwordx4 v[216:219], v[86:87], off
	v_addc_co_u32_e32 v85, vcc, 0, v79, vcc
	global_load_dwordx4 v[220:223], v[88:89], off offset:-4096
	global_load_dwordx4 v[224:227], v[88:89], off
	global_load_dwordx4 v[228:231], v[84:85], off
	s_waitcnt vmcnt(3)
	v_mfma_f32_16x16x32_bf16 v[28:31], v[64:67], v[216:219], v[28:31]
	s_waitcnt vmcnt(2)
	v_mfma_f32_16x16x32_bf16 v[20:23], v[64:67], v[220:223], v[20:23]
	s_waitcnt vmcnt(1)
	v_mfma_f32_16x16x32_bf16 v[12:15], v[64:67], v[224:227], v[12:15]
	s_waitcnt vmcnt(0)
	v_mfma_f32_16x16x32_bf16 v[4:7], v[64:67], v[228:231], v[4:7]
	v_add_co_u32_e32 v64, vcc, s2, v82
	s_nop 1
	v_addc_co_u32_e32 v65, vcc, 0, v83, vcc
	v_add_co_u32_e32 v82, vcc, s90, v82
	s_nop 1
	v_addc_co_u32_e32 v83, vcc, 0, v83, vcc
	global_load_dwordx4 v[64:67], v[64:65], off
	s_nop 0
	global_load_dwordx4 v[94:97], v[82:83], off offset:3072
	s_waitcnt vmcnt(0)
	v_and_b32_e32 v83, 0xffff0000, v94
	v_lshlrev_b32_e32 v82, 16, v94
	v_pk_add_f32 v[82:83], v[82:83], 0 op_sel_hi:[1,0]
	v_and_b32_e32 v99, 0xffff0000, v64
	v_lshlrev_b32_e32 v98, 16, v64
	v_pk_add_f32 v[82:83], v[82:83], v[98:99]
	v_lshlrev_b32_e32 v94, 16, v65
	v_pk_fma_f32 v[82:83], v[82:83], 0.5, v[98:99] op_sel_hi:[1,0,1] neg_lo:[0,0,1] neg_hi:[0,0,1]
	s_nop 0
	v_cvt_pk_bf16_f32 v64, v82, v83
	v_and_b32_e32 v83, 0xffff0000, v95
	v_lshlrev_b32_e32 v82, 16, v95
	v_pk_add_f32 v[82:83], v[82:83], 0 op_sel_hi:[1,0]
	v_and_b32_e32 v95, 0xffff0000, v65
	v_pk_add_f32 v[82:83], v[82:83], v[94:95]
	s_nop 0
	v_pk_fma_f32 v[82:83], v[82:83], 0.5, v[94:95] op_sel_hi:[1,0,1] neg_lo:[0,0,1] neg_hi:[0,0,1]
	v_and_b32_e32 v95, 0xffff0000, v66
	v_cvt_pk_bf16_f32 v65, v82, v83
	v_and_b32_e32 v83, 0xffff0000, v96
	v_lshlrev_b32_e32 v82, 16, v96
	v_pk_add_f32 v[82:83], v[82:83], 0 op_sel_hi:[1,0]
	v_lshlrev_b32_e32 v94, 16, v66
	v_pk_add_f32 v[82:83], v[82:83], v[94:95]
	s_nop 0
	v_pk_fma_f32 v[82:83], v[82:83], 0.5, v[94:95] op_sel_hi:[1,0,1] neg_lo:[0,0,1] neg_hi:[0,0,1]
	v_and_b32_e32 v95, 0xffff0000, v67
	v_cvt_pk_bf16_f32 v66, v82, v83
	v_and_b32_e32 v83, 0xffff0000, v97
	v_lshlrev_b32_e32 v82, 16, v97
	v_pk_add_f32 v[82:83], v[82:83], 0 op_sel_hi:[1,0]
	v_lshlrev_b32_e32 v94, 16, v67
	v_pk_add_f32 v[82:83], v[82:83], v[94:95]
	s_nop 0
	v_pk_fma_f32 v[82:83], v[82:83], 0.5, v[94:95] op_sel_hi:[1,0,1] neg_lo:[0,0,1] neg_hi:[0,0,1]
	global_load_dwordx4 v[94:97], v[78:79], off
	v_cvt_pk_bf16_f32 v67, v82, v83
	s_waitcnt vmcnt(0)
	s_nop 0
	v_mfma_f32_16x16x32_bf16 v[56:59], v[64:67], v[94:97], v[56:59]
	global_load_dwordx4 v[216:219], v[80:81], off offset:-4096
	s_nop 0
	global_load_dwordx4 v[220:223], v[80:81], off
	global_load_dwordx4 v[224:227], v[86:87], off offset:-4096
	global_load_dwordx4 v[228:231], v[86:87], off
	global_load_dwordx4 v[232:235], v[88:89], off offset:-4096
	global_load_dwordx4 v[236:239], v[84:85], off offset:-4096
	global_load_dwordx4 v[240:243], v[84:85], off
	s_waitcnt vmcnt(5)
	v_mfma_f32_16x16x32_bf16 v[40:43], v[64:67], v[220:223], v[40:43]
	v_mfma_f32_16x16x32_bf16 v[48:51], v[64:67], v[216:219], v[48:51]
	s_waitcnt vmcnt(4)
	v_mfma_f32_16x16x32_bf16 v[32:35], v[64:67], v[224:227], v[32:35]
	s_waitcnt vmcnt(3)
	v_mfma_f32_16x16x32_bf16 v[24:27], v[64:67], v[228:231], v[24:27]
	s_waitcnt vmcnt(2)
	v_mfma_f32_16x16x32_bf16 v[16:19], v[64:67], v[232:235], v[16:19]
	s_waitcnt vmcnt(1)
	v_mfma_f32_16x16x32_bf16 v[8:11], v[64:67], v[236:239], v[8:11]
	s_waitcnt vmcnt(0)
	v_mfma_f32_16x16x32_bf16 v[0:3], v[64:67], v[240:243], v[0:3]
	s_add_u32 s36, s36, 64
	s_addc_u32 s37, s37, 0
	s_cmpk_lg_i32 s36, 0x100
	s_cbranch_scc1 .LBB0_1165
; template <int W>
; __device__ __forceinline__ void pool_tile(const Params& p, int row0, int g, int wave, int lane_in) {
;     ...
; #pragma unroll
;   for (int n = 0; n < 8; n++) {
;     float cs = p.c_scale[g * 128 + n * 16 + fr];
; #pragma unroll
;     for (int m = 0; m < 2; m++)
; #pragma unroll
;       for (int j = 0; j < 4; j++) {
;         size_t row = (size_t)row0 + wave * 32 + m * 16 + fq * 4 + j;
;         p.mix[row * D + g * 128 + n * 16 + fr] = f2bf(acc[m][n][j] * cs);
;       }
;   }
	s_ashr_i32 s55, s54, 31
	v_lshlrev_b32_e32 v64, 2, v91
	v_readlane_b32 s60, v255, 10
	s_or_b64 s[4:5], s[54:55], s[0:1]
	v_ashrrev_i32_e32 v65, 31, v64
	v_lshlrev_b32_e32 v92, 1, v90
	v_readlane_b32 s61, v255, 11
	v_readlane_b32 s62, v255, 12
	v_readlane_b32 s63, v255, 13
	v_readlane_b32 s64, v255, 14
	v_readlane_b32 s65, v255, 15
	v_readlane_b32 s66, v255, 16
	v_readlane_b32 s67, v255, 17
	v_readlane_b32 s68, v255, 18
	v_readlane_b32 s69, v255, 19
	v_readlane_b32 s70, v255, 20
	v_readlane_b32 s71, v255, 21
	v_readlane_b32 s72, v255, 22
	v_readlane_b32 s73, v255, 23
	v_readlane_b32 s74, v255, 24
	v_readlane_b32 s75, v255, 25
	v_lshl_add_u64 v[66:67], s[4:5], 0, v[64:65]
	v_lshl_add_u64 v[64:65], s[68:69], 0, v[92:93]
	v_readlane_b32 s60, v254, 38
	v_lshlrev_b32_e32 v72, 2, v90
	v_readlane_b32 s68, v254, 46
	v_readlane_b32 s69, v254, 47
	v_lshlrev_b64 v[66:67], 11, v[66:67]
	v_lshl_add_u64 v[68:69], v[64:65], 0, v[66:67]
	v_or_b32_e32 v70, 0x1000, v66
	v_mov_b32_e32 v71, v67
	v_or_b32_e32 v66, 0x1800, v66
	global_load_dword v73, v72, s[68:69]
	s_mov_b64 s[36:37], 0
	v_readlane_b32 s61, v254, 39
	v_readlane_b32 s62, v254, 40
	v_readlane_b32 s63, v254, 41
	v_readlane_b32 s64, v254, 42
	v_readlane_b32 s65, v254, 43
	v_readlane_b32 s66, v254, 44
	v_readlane_b32 s67, v254, 45
	v_readlane_b32 s70, v254, 48
	v_readlane_b32 s71, v254, 49
	v_readlane_b32 s72, v254, 50
	v_readlane_b32 s73, v254, 51
	v_readlane_b32 s74, v254, 52
	v_readlane_b32 s75, v254, 53
	s_waitcnt vmcnt(0)
	v_mul_f32_e32 v60, v60, v73
	v_cvt_pk_bf16_f32 v60, v60, s0
	global_store_short v[68:69], v60, off
	v_mul_f32_e32 v60, v61, v73
	v_cvt_pk_bf16_f32 v60, v60, s0
	global_store_short v[68:69], v60, off offset:2048
	v_mul_f32_e32 v60, v62, v73
	v_cvt_pk_bf16_f32 v62, v60, s0
	v_lshl_add_u64 v[60:61], v[64:65], 0, v[70:71]
	global_store_short v[60:61], v62, off
	v_mul_f32_e32 v60, v63, v73
	v_cvt_pk_bf16_f32 v62, v60, s0
	v_lshl_add_u64 v[60:61], v[64:65], 0, v[66:67]
	global_store_short v[60:61], v62, off
	v_add_co_u32_e32 v62, vcc, s91, v68
	v_mul_f32_e32 v56, v56, v73
	s_nop 0
	v_addc_co_u32_e32 v63, vcc, 0, v69, vcc
	v_add_co_u32_e32 v60, vcc, s92, v68
	v_cvt_pk_bf16_f32 v56, v56, s0
	s_nop 0
	v_addc_co_u32_e32 v61, vcc, 0, v69, vcc
	global_store_short v[60:61], v56, off offset:-4096
	v_mul_f32_e32 v56, v57, v73
	v_cvt_pk_bf16_f32 v56, v56, s0
	global_store_short v[62:63], v56, off offset:2048
	v_mul_f32_e32 v56, v58, v73
	global_load_dword v58, v72, s[68:69] offset:64
	v_cvt_pk_bf16_f32 v56, v56, s0
	global_store_short v[60:61], v56, off
	v_mul_f32_e32 v56, v59, v73
	v_cvt_pk_bf16_f32 v56, v56, s0
	global_store_short v[60:61], v56, off offset:2048
	v_lshl_add_u64 v[56:57], v[64:65], 0, 32
	s_waitcnt vmcnt(2)
	v_mul_f32_e32 v48, v48, v58
	v_cvt_pk_bf16_f32 v48, v48, s0
	global_store_short v[62:63], v48, off offset:32
	v_mul_f32_e32 v48, v49, v58
	v_cvt_pk_bf16_f32 v48, v48, s0
	global_store_short v[62:63], v48, off offset:2080
	v_mul_f32_e32 v48, v50, v58
	global_load_dword v50, v72, s[68:69] offset:128
	v_mul_f32_e32 v52, v52, v58
	v_cvt_pk_bf16_f32 v52, v52, s0
	v_cvt_pk_bf16_f32 v48, v48, s0
	global_store_short v[68:69], v52, off offset:32
	v_mul_f32_e32 v52, v53, v58
	global_store_short v[60:61], v48, off offset:32
	v_mul_f32_e32 v48, v51, v58
	v_cvt_pk_bf16_f32 v52, v52, s0
	v_cvt_pk_bf16_f32 v48, v48, s0
	global_store_short v[68:69], v52, off offset:2080
	v_mul_f32_e32 v52, v54, v58
	global_store_short v[60:61], v48, off offset:2080
	v_lshl_add_u64 v[48:49], v[64:65], 0, 64
	v_cvt_pk_bf16_f32 v54, v52, s0
	v_lshl_add_u64 v[52:53], v[56:57], 0, v[70:71]
	global_store_short v[52:53], v54, off
	v_mul_f32_e32 v52, v55, v58
	v_cvt_pk_bf16_f32 v54, v52, s0
	v_lshl_add_u64 v[52:53], v[56:57], 0, v[66:67]
	global_store_short v[52:53], v54, off
	s_waitcnt vmcnt(6)
	v_mul_f32_e32 v40, v40, v50
	v_cvt_pk_bf16_f32 v40, v40, s0
	global_store_short v[62:63], v40, off offset:64
	v_mul_f32_e32 v40, v41, v50
	v_cvt_pk_bf16_f32 v40, v40, s0
	global_store_short v[62:63], v40, off offset:2112
	v_mul_f32_e32 v40, v42, v50
	global_load_dword v42, v72, s[68:69] offset:192
	v_mul_f32_e32 v44, v44, v50
	v_cvt_pk_bf16_f32 v44, v44, s0
	v_cvt_pk_bf16_f32 v40, v40, s0
	global_store_short v[68:69], v44, off offset:64
	v_mul_f32_e32 v44, v45, v50
	global_store_short v[60:61], v40, off offset:64
	v_mul_f32_e32 v40, v43, v50
	v_cvt_pk_bf16_f32 v44, v44, s0
	v_cvt_pk_bf16_f32 v40, v40, s0
	global_store_short v[68:69], v44, off offset:2112
	v_mul_f32_e32 v44, v46, v50
	global_store_short v[60:61], v40, off offset:2112
	v_lshl_add_u64 v[40:41], v[64:65], 0, s[42:43]
	v_cvt_pk_bf16_f32 v46, v44, s0
	v_lshl_add_u64 v[44:45], v[48:49], 0, v[70:71]
	global_store_short v[44:45], v46, off
	v_mul_f32_e32 v44, v47, v50
	v_cvt_pk_bf16_f32 v46, v44, s0
	v_lshl_add_u64 v[44:45], v[48:49], 0, v[66:67]
	global_store_short v[44:45], v46, off
	s_waitcnt vmcnt(6)
; template <int W>
; __device__ __forceinline__ void pool_tile(const Params& p, int row0, int g, int wave, int lane_in) {
;     ...
; #pragma unroll
;   for (int n = 0; n < 8; n++) {
;     float cs = p.c_scale[g * 128 + n * 16 + fr];
; #pragma unroll
;     for (int m = 0; m < 2; m++)
; #pragma unroll
;       for (int j = 0; j < 4; j++) {
;         size_t row = (size_t)row0 + wave * 32 + m * 16 + fq * 4 + j;
;         p.mix[row * D + g * 128 + n * 16 + fr] = f2bf(acc[m][n][j] * cs);
;       }
;   }
	v_mul_f32_e32 v32, v32, v42
	v_cvt_pk_bf16_f32 v32, v32, s0
	global_store_short v[62:63], v32, off offset:96
	v_mul_f32_e32 v32, v33, v42
	v_cvt_pk_bf16_f32 v32, v32, s0
	global_store_short v[62:63], v32, off offset:2144
	v_mul_f32_e32 v32, v34, v42
	global_load_dword v34, v72, s[68:69] offset:256
	v_mul_f32_e32 v36, v36, v42
	v_cvt_pk_bf16_f32 v36, v36, s0
	v_cvt_pk_bf16_f32 v32, v32, s0
	global_store_short v[68:69], v36, off offset:96
	v_mul_f32_e32 v36, v37, v42
	global_store_short v[60:61], v32, off offset:96
	v_mul_f32_e32 v32, v35, v42
	v_cvt_pk_bf16_f32 v36, v36, s0
	v_cvt_pk_bf16_f32 v32, v32, s0
	global_store_short v[68:69], v36, off offset:2144
	v_mul_f32_e32 v36, v38, v42
	global_store_short v[60:61], v32, off offset:2144
	v_lshl_add_u64 v[32:33], v[64:65], 0, s[44:45]
	v_cvt_pk_bf16_f32 v38, v36, s0
	v_lshl_add_u64 v[36:37], v[40:41], 0, v[70:71]
	global_store_short v[36:37], v38, off
	v_mul_f32_e32 v36, v39, v42
	v_cvt_pk_bf16_f32 v38, v36, s0
	v_lshl_add_u64 v[36:37], v[40:41], 0, v[66:67]
	global_store_short v[36:37], v38, off
	s_waitcnt vmcnt(6)
	v_mul_f32_e32 v24, v24, v34
	v_cvt_pk_bf16_f32 v24, v24, s0
	global_store_short v[62:63], v24, off offset:128
	v_mul_f32_e32 v24, v25, v34
	v_cvt_pk_bf16_f32 v24, v24, s0
	global_store_short v[62:63], v24, off offset:2176
	v_mul_f32_e32 v24, v26, v34
	global_load_dword v26, v72, s[68:69] offset:320
	v_mul_f32_e32 v28, v28, v34
	v_cvt_pk_bf16_f32 v28, v28, s0
	v_cvt_pk_bf16_f32 v24, v24, s0
	global_store_short v[68:69], v28, off offset:128
	v_mul_f32_e32 v28, v29, v34
	global_store_short v[60:61], v24, off offset:128
	v_mul_f32_e32 v24, v27, v34
	v_cvt_pk_bf16_f32 v28, v28, s0
	v_cvt_pk_bf16_f32 v24, v24, s0
	global_store_short v[68:69], v28, off offset:2176
	v_mul_f32_e32 v28, v30, v34
	global_store_short v[60:61], v24, off offset:2176
	v_lshl_add_u64 v[24:25], v[64:65], 0, s[46:47]
	v_cvt_pk_bf16_f32 v30, v28, s0
	v_lshl_add_u64 v[28:29], v[32:33], 0, v[70:71]
	global_store_short v[28:29], v30, off
	v_mul_f32_e32 v28, v31, v34
	v_cvt_pk_bf16_f32 v30, v28, s0
	v_lshl_add_u64 v[28:29], v[32:33], 0, v[66:67]
	global_store_short v[28:29], v30, off
	s_waitcnt vmcnt(6)
	v_mul_f32_e32 v16, v16, v26
	v_cvt_pk_bf16_f32 v16, v16, s0
	global_store_short v[62:63], v16, off offset:160
	v_mul_f32_e32 v16, v17, v26
	v_cvt_pk_bf16_f32 v16, v16, s0
	global_store_short v[62:63], v16, off offset:2208
	v_mul_f32_e32 v16, v18, v26
	global_load_dword v18, v72, s[68:69] offset:384
	v_mul_f32_e32 v20, v20, v26
	v_cvt_pk_bf16_f32 v20, v20, s0
	v_cvt_pk_bf16_f32 v16, v16, s0
	global_store_short v[68:69], v20, off offset:160
	v_mul_f32_e32 v20, v21, v26
	global_store_short v[60:61], v16, off offset:160
	v_mul_f32_e32 v16, v19, v26
	v_cvt_pk_bf16_f32 v20, v20, s0
	v_cvt_pk_bf16_f32 v16, v16, s0
	global_store_short v[68:69], v20, off offset:2208
	v_mul_f32_e32 v20, v22, v26
	global_store_short v[60:61], v16, off offset:2208
	v_lshl_add_u64 v[16:17], v[64:65], 0, s[48:49]
	v_cvt_pk_bf16_f32 v22, v20, s0
	v_lshl_add_u64 v[20:21], v[24:25], 0, v[70:71]
	global_store_short v[20:21], v22, off
	v_mul_f32_e32 v20, v23, v26
	v_cvt_pk_bf16_f32 v22, v20, s0
	v_lshl_add_u64 v[20:21], v[24:25], 0, v[66:67]
	global_store_short v[20:21], v22, off
	s_waitcnt vmcnt(6)
	v_mul_f32_e32 v8, v8, v18
	v_cvt_pk_bf16_f32 v8, v8, s0
	global_store_short v[62:63], v8, off offset:192
	v_mul_f32_e32 v8, v9, v18
	v_cvt_pk_bf16_f32 v8, v8, s0
	global_store_short v[62:63], v8, off offset:2240
	v_mul_f32_e32 v8, v10, v18
	v_cvt_pk_bf16_f32 v8, v8, s0
	global_store_short v[60:61], v8, off offset:192
	v_mul_f32_e32 v8, v11, v18
	v_cvt_pk_bf16_f32 v8, v8, s0
	global_store_short v[60:61], v8, off offset:2240
	global_load_dword v8, v72, s[68:69] offset:448
	v_mul_f32_e32 v12, v12, v18
	v_cvt_pk_bf16_f32 v12, v12, s0
	global_store_short v[68:69], v12, off offset:192
	v_mul_f32_e32 v12, v13, v18
	v_cvt_pk_bf16_f32 v12, v12, s0
	global_store_short v[68:69], v12, off offset:2240
	v_mul_f32_e32 v12, v14, v18
	v_lshl_add_u64 v[10:11], v[64:65], 0, s[50:51]
	v_cvt_pk_bf16_f32 v14, v12, s0
	v_lshl_add_u64 v[12:13], v[16:17], 0, v[70:71]
	global_store_short v[12:13], v14, off
	v_mul_f32_e32 v12, v15, v18
	v_cvt_pk_bf16_f32 v14, v12, s0
	v_lshl_add_u64 v[12:13], v[16:17], 0, v[66:67]
	global_store_short v[12:13], v14, off
	s_waitcnt vmcnt(4)
	v_mul_f32_e32 v4, v4, v8
	v_mul_f32_e32 v0, v0, v8
	v_cvt_pk_bf16_f32 v4, v4, s0
	v_cvt_pk_bf16_f32 v0, v0, s0
	global_store_short v[68:69], v4, off offset:224
	v_mul_f32_e32 v4, v5, v8
	global_store_short v[62:63], v0, off offset:224
	v_mul_f32_e32 v0, v1, v8
	v_cvt_pk_bf16_f32 v4, v4, s0
	v_cvt_pk_bf16_f32 v0, v0, s0
	global_store_short v[68:69], v4, off offset:2272
	v_mul_f32_e32 v4, v6, v8
	global_store_short v[62:63], v0, off offset:2272
	v_mul_f32_e32 v0, v2, v8
	v_cvt_pk_bf16_f32 v6, v4, s0
	v_lshl_add_u64 v[4:5], v[10:11], 0, v[70:71]
	v_cvt_pk_bf16_f32 v0, v0, s0
	global_store_short v[4:5], v6, off
	v_mul_f32_e32 v4, v7, v8
	global_store_short v[60:61], v0, off offset:224
	v_mul_f32_e32 v0, v3, v8
	v_cvt_pk_bf16_f32 v6, v4, s0
	v_lshl_add_u64 v[4:5], v[10:11], 0, v[66:67]
	v_cvt_pk_bf16_f32 v0, v0, s0
	global_store_short v[4:5], v6, off
	global_store_short v[60:61], v0, off offset:2272

; __device__ __forceinline__ float bf2f(bfr h) { return __uint_as_float(((unsigned)h) << 16); }
; template <int W>
; __device__ __forceinline__ void pool_tile(const Params& p, int row0, int g, int wave, int lane_in) {
;     ...
;       bf16x8 xc = *(const bf16x8*)(colp + (size_t)tt * 512);
; #pragma unroll
;       for (int o0 = 0; o0 < W; o0 += WC) {
;         bf16x8 wv[WC];
; #pragma unroll
;         for (int o = 0; o < WC; o++) {
;           int rc = min(max(tt - W / 2 + o0 + o, 0), S - 1);
;           wv[o] = *(const bf16x8*)(colp + (size_t)rc * 512);
;         }
; #pragma unroll
;         for (int o = 0; o < WC; o++) {
;           int r = tt - W / 2 + o0 + o;
;           float wgt = (r >= 0 && r < S) ? 1.f : 0.f;
; #pragma unroll
;           for (int e = 0; e < 8; e++) sum[e] += wgt * bf2f((bfr)wv[o][e]);
;         }
;         __builtin_amdgcn_sched_barrier(0);
;       }
;       float invn = 1.f / (float)(hi - lo);
;       u32x4 pk;
; #pragma unroll
;       for (int e = 0; e < 4; e++)
;         pk[e] = pack2(sum[2 * e] * invn - bf2f((bfr)xc[2 * e]), sum[2 * e + 1] * invn - bf2f((bfr)xc[2 * e + 1]));
;       bf16x8 af = __builtin_bit_cast(bf16x8, pk);
; #pragma unroll
;       for (int n = 0; n < 8; n++) {
;         bf16x8 bfg = *(const bf16x8*)(wp + (size_t)(n * 16 + fr) * 128 + ks * 32 + fq * 8);
;         acc[m][n] = mfma16(af, bfg, acc[m][n]);
;       }
.LBB0_1169:
	v_lshl_add_u64 v[64:65], v[86:87], 0, s[36:37]
	v_lshl_add_u64 v[96:97], v[82:83], 0, s[36:37]
	v_lshl_add_u64 v[90:91], v[84:85], 0, s[36:37]
	global_load_dwordx4 v[64:67], v[64:65], off
	s_nop 0
	global_load_dwordx4 v[104:107], v[90:91], off
	global_load_dwordx4 v[108:111], v[96:97], off offset:256
	global_load_dwordx4 v[112:115], v[96:97], off offset:1280
	v_lshl_add_u64 v[100:101], v[88:89], 0, s[36:37]
	s_waitcnt vmcnt(3)
	v_and_b32_e32 v91, 0xffff0000, v64
	v_lshlrev_b32_e32 v90, 16, v64
	v_pk_fma_f32 v[90:91], v[68:69], v[90:91], 0 op_sel_hi:[1,1,0]
	s_waitcnt vmcnt(2)
	v_and_b32_e32 v95, 0xffff0000, v104
	v_lshlrev_b32_e32 v94, 16, v104
	v_pk_fma_f32 v[90:91], v[70:71], v[94:95], v[90:91]
	s_waitcnt vmcnt(1)
	v_and_b32_e32 v95, 0xffff0000, v108
	v_lshlrev_b32_e32 v94, 16, v108
	v_pk_add_f32 v[90:91], v[90:91], v[94:95]
	s_waitcnt vmcnt(0)
	v_and_b32_e32 v99, 0xffff0000, v112
	v_lshlrev_b32_e32 v98, 16, v112
	v_pk_add_f32 v[90:91], v[90:91], v[98:99]
	v_and_b32_e32 v99, 0xffff0000, v113
	v_pk_fma_f32 v[90:91], v[72:73], v[90:91], v[94:95] neg_lo:[0,0,1] neg_hi:[0,0,1]
	v_and_b32_e32 v95, 0xffff0000, v105
	v_cvt_pk_bf16_f32 v64, v90, v91
	v_and_b32_e32 v91, 0xffff0000, v65
	v_lshlrev_b32_e32 v90, 16, v65
	v_pk_fma_f32 v[90:91], v[68:69], v[90:91], 0 op_sel_hi:[1,1,0]
	v_lshlrev_b32_e32 v94, 16, v105
	v_pk_fma_f32 v[90:91], v[70:71], v[94:95], v[90:91]
	v_and_b32_e32 v95, 0xffff0000, v109
	v_lshlrev_b32_e32 v94, 16, v109
	v_pk_add_f32 v[90:91], v[90:91], v[94:95]
	v_lshlrev_b32_e32 v98, 16, v113
	v_pk_add_f32 v[90:91], v[90:91], v[98:99]
	v_and_b32_e32 v99, 0xffff0000, v114
	v_pk_fma_f32 v[90:91], v[72:73], v[90:91], v[94:95] neg_lo:[0,0,1] neg_hi:[0,0,1]
	v_and_b32_e32 v95, 0xffff0000, v106
	v_cvt_pk_bf16_f32 v65, v90, v91
	v_and_b32_e32 v91, 0xffff0000, v66
	v_lshlrev_b32_e32 v90, 16, v66
	v_pk_fma_f32 v[90:91], v[68:69], v[90:91], 0 op_sel_hi:[1,1,0]
	v_lshlrev_b32_e32 v94, 16, v106
	v_pk_fma_f32 v[90:91], v[70:71], v[94:95], v[90:91]
	v_and_b32_e32 v95, 0xffff0000, v110
	v_lshlrev_b32_e32 v94, 16, v110
	v_pk_add_f32 v[90:91], v[90:91], v[94:95]
	v_lshlrev_b32_e32 v98, 16, v114
	v_pk_add_f32 v[90:91], v[90:91], v[98:99]
	v_and_b32_e32 v99, 0xffff0000, v115
	v_pk_fma_f32 v[90:91], v[72:73], v[90:91], v[94:95] neg_lo:[0,0,1] neg_hi:[0,0,1]
	v_and_b32_e32 v95, 0xffff0000, v107
	v_cvt_pk_bf16_f32 v66, v90, v91
	v_and_b32_e32 v91, 0xffff0000, v67
	v_lshlrev_b32_e32 v90, 16, v67
	v_pk_fma_f32 v[90:91], v[68:69], v[90:91], 0 op_sel_hi:[1,1,0]
	v_lshlrev_b32_e32 v94, 16, v107
	v_pk_fma_f32 v[90:91], v[70:71], v[94:95], v[90:91]
	v_and_b32_e32 v95, 0xffff0000, v111
	v_lshlrev_b32_e32 v94, 16, v111
	v_pk_add_f32 v[90:91], v[90:91], v[94:95]
	v_lshlrev_b32_e32 v98, 16, v115
	v_pk_add_f32 v[90:91], v[90:91], v[98:99]
	s_mov_b32 s3, 0xb000
	v_pk_fma_f32 v[90:91], v[72:73], v[90:91], v[94:95] neg_lo:[0,0,1] neg_hi:[0,0,1]
	v_add_co_u32_e32 v94, vcc, s92, v100
	v_cvt_pk_bf16_f32 v67, v90, v91
	s_nop 0
	v_addc_co_u32_e32 v95, vcc, 0, v101, vcc
	global_load_dwordx4 v[216:219], v[94:95], off offset:-4096
	v_add_co_u32_e32 v90, vcc, s3, v100
	s_mov_b32 s3, 0xd000
	s_nop 0
	v_addc_co_u32_e32 v91, vcc, 0, v101, vcc
	v_add_co_u32_e32 v98, vcc, s3, v100
	s_mov_b32 s3, 0xf000
	s_nop 0
	v_addc_co_u32_e32 v99, vcc, 0, v101, vcc
	v_add_co_u32_e32 v100, vcc, s3, v100
	global_load_dwordx4 v[220:223], v[94:95], off
	v_addc_co_u32_e32 v101, vcc, 0, v101, vcc
	global_load_dwordx4 v[224:227], v[90:91], off offset:-4096
	global_load_dwordx4 v[228:231], v[90:91], off
	global_load_dwordx4 v[232:235], v[98:99], off offset:-4096
	global_load_dwordx4 v[236:239], v[98:99], off
	global_load_dwordx4 v[240:243], v[100:101], off offset:-4096
	global_load_dwordx4 v[244:247], v[100:101], off
	s_waitcnt vmcnt(7)
	v_mfma_f32_16x16x32_bf16 v[60:63], v[64:67], v[216:219], v[60:63]
	s_waitcnt vmcnt(6)
	v_mfma_f32_16x16x32_bf16 v[52:55], v[64:67], v[220:223], v[52:55]
	s_waitcnt vmcnt(5)
	v_mfma_f32_16x16x32_bf16 v[44:47], v[64:67], v[224:227], v[44:47]
	s_waitcnt vmcnt(4)
	v_mfma_f32_16x16x32_bf16 v[36:39], v[64:67], v[228:231], v[36:39]
	s_waitcnt vmcnt(3)
	v_mfma_f32_16x16x32_bf16 v[28:31], v[64:67], v[232:235], v[28:31]
	s_waitcnt vmcnt(2)
	v_mfma_f32_16x16x32_bf16 v[20:23], v[64:67], v[236:239], v[20:23]
	s_waitcnt vmcnt(1)
	v_mfma_f32_16x16x32_bf16 v[12:15], v[64:67], v[240:243], v[12:15]
	s_waitcnt vmcnt(0)
	v_mfma_f32_16x16x32_bf16 v[4:7], v[64:67], v[244:247], v[4:7]
	v_add_co_u32_e32 v96, vcc, s90, v96
	v_lshl_add_u64 v[64:65], v[80:81], 0, s[36:37]
	s_nop 0
	v_addc_co_u32_e32 v97, vcc, 0, v97, vcc
	v_lshl_add_u64 v[112:113], v[78:79], 0, s[36:37]
	global_load_dwordx4 v[64:67], v[64:65], off
	s_nop 0
	global_load_dwordx4 v[104:107], v[96:97], off offset:2304
	global_load_dwordx4 v[108:111], v[96:97], off offset:3328
	s_nop 0
	global_load_dwordx4 v[112:115], v[112:113], off
	s_waitcnt vmcnt(2)
	v_and_b32_e32 v97, 0xffff0000, v104
	v_lshlrev_b32_e32 v96, 16, v104
	v_pk_add_f32 v[96:97], v[96:97], 0 op_sel_hi:[1,0]
	s_waitcnt vmcnt(1)
	v_and_b32_e32 v117, 0xffff0000, v108
	v_lshlrev_b32_e32 v116, 16, v108
	v_pk_add_f32 v[96:97], v[96:97], v[116:117]
	v_and_b32_e32 v117, 0xffff0000, v64
	v_lshlrev_b32_e32 v116, 16, v64
	v_pk_add_f32 v[96:97], v[96:97], v[116:117]
	s_waitcnt vmcnt(0)
; __device__ __forceinline__ float bf2f(bfr h) { return __uint_as_float(((unsigned)h) << 16); }
; template <int W>
; __device__ __forceinline__ void pool_tile(const Params& p, int row0, int g, int wave, int lane_in) {
;     ...
;       bf16x8 xc = *(const bf16x8*)(colp + (size_t)tt * 512);
; #pragma unroll
;       for (int o0 = 0; o0 < W; o0 += WC) {
;         bf16x8 wv[WC];
; #pragma unroll
;         for (int o = 0; o < WC; o++) {
;           int rc = min(max(tt - W / 2 + o0 + o, 0), S - 1);
;           wv[o] = *(const bf16x8*)(colp + (size_t)rc * 512);
;         }
; #pragma unroll
;         for (int o = 0; o < WC; o++) {
;           int r = tt - W / 2 + o0 + o;
;           float wgt = (r >= 0 && r < S) ? 1.f : 0.f;
; #pragma unroll
;           for (int e = 0; e < 8; e++) sum[e] += wgt * bf2f((bfr)wv[o][e]);
;         }
;         __builtin_amdgcn_sched_barrier(0);
;       }
;       float invn = 1.f / (float)(hi - lo);
;       u32x4 pk;
; #pragma unroll
;       for (int e = 0; e < 4; e++)
;         pk[e] = pack2(sum[2 * e] * invn - bf2f((bfr)xc[2 * e]), sum[2 * e + 1] * invn - bf2f((bfr)xc[2 * e + 1]));
;       bf16x8 af = __builtin_bit_cast(bf16x8, pk);
; #pragma unroll
;       for (int n = 0; n < 8; n++) {
;         bf16x8 bfg = *(const bf16x8*)(wp + (size_t)(n * 16 + fr) * 128 + ks * 32 + fq * 8);
;         acc[m][n] = mfma16(af, bfg, acc[m][n]);
;       }
;       __builtin_amdgcn_sched_barrier(0);
;     }
;   }
; #pragma unroll
;   for (int n = 0; n < 8; n++) {
;     float cs = p.c_scale[g * 128 + n * 16 + fr];
; #pragma unroll
;     for (int m = 0; m < 2; m++)
; #pragma unroll
;       for (int j = 0; j < 4; j++) {
;         size_t row = (size_t)row0 + wave * 32 + m * 16 + fq * 4 + j;
;         p.mix[row * D + g * 128 + n * 16 + fr] = f2bf(acc[m][n][j] * cs);
;       }
;   }
	v_and_b32_e32 v119, 0xffff0000, v112
	v_lshlrev_b32_e32 v118, 16, v112
	v_pk_fma_f32 v[96:97], v[74:75], v[118:119], v[96:97]
	v_lshlrev_b32_e32 v104, 16, v109
	v_pk_fma_f32 v[96:97], v[76:77], v[96:97], v[116:117] neg_lo:[0,0,1] neg_hi:[0,0,1]
	v_lshlrev_b32_e32 v108, 16, v113
	v_cvt_pk_bf16_f32 v64, v96, v97
	v_and_b32_e32 v97, 0xffff0000, v105
	v_lshlrev_b32_e32 v96, 16, v105
	v_pk_add_f32 v[96:97], v[96:97], 0 op_sel_hi:[1,0]
	v_and_b32_e32 v105, 0xffff0000, v109
	v_pk_add_f32 v[96:97], v[96:97], v[104:105]
	v_and_b32_e32 v105, 0xffff0000, v65
	v_lshlrev_b32_e32 v104, 16, v65
	v_pk_add_f32 v[96:97], v[96:97], v[104:105]
	v_and_b32_e32 v109, 0xffff0000, v113
	v_pk_fma_f32 v[96:97], v[74:75], v[108:109], v[96:97]
	v_and_b32_e32 v109, 0xffff0000, v114
	v_pk_fma_f32 v[96:97], v[76:77], v[96:97], v[104:105] neg_lo:[0,0,1] neg_hi:[0,0,1]
	v_and_b32_e32 v105, 0xffff0000, v110
	v_cvt_pk_bf16_f32 v65, v96, v97
	v_and_b32_e32 v97, 0xffff0000, v106
	v_lshlrev_b32_e32 v96, 16, v106
	v_pk_add_f32 v[96:97], v[96:97], 0 op_sel_hi:[1,0]
	v_lshlrev_b32_e32 v104, 16, v110
	v_pk_add_f32 v[96:97], v[96:97], v[104:105]
	v_and_b32_e32 v105, 0xffff0000, v66
	v_lshlrev_b32_e32 v104, 16, v66
	v_pk_add_f32 v[96:97], v[96:97], v[104:105]
	v_lshlrev_b32_e32 v108, 16, v114
	v_pk_fma_f32 v[96:97], v[74:75], v[108:109], v[96:97]
	v_lshlrev_b32_e32 v106, 16, v115
	v_pk_fma_f32 v[96:97], v[76:77], v[96:97], v[104:105] neg_lo:[0,0,1] neg_hi:[0,0,1]
	v_and_b32_e32 v105, 0xffff0000, v111
	v_cvt_pk_bf16_f32 v66, v96, v97
	v_and_b32_e32 v97, 0xffff0000, v107
	v_lshlrev_b32_e32 v96, 16, v107
	v_pk_add_f32 v[96:97], v[96:97], 0 op_sel_hi:[1,0]
	v_lshlrev_b32_e32 v104, 16, v111
	v_pk_add_f32 v[96:97], v[96:97], v[104:105]
	v_and_b32_e32 v105, 0xffff0000, v67
	v_lshlrev_b32_e32 v104, 16, v67
	v_pk_add_f32 v[96:97], v[96:97], v[104:105]
	v_and_b32_e32 v107, 0xffff0000, v115
	v_pk_fma_f32 v[96:97], v[74:75], v[106:107], v[96:97]
	s_nop 0
	v_pk_fma_f32 v[96:97], v[76:77], v[96:97], v[104:105] neg_lo:[0,0,1] neg_hi:[0,0,1]
	global_load_dwordx4 v[104:107], v[94:95], off offset:-4096
	v_cvt_pk_bf16_f32 v67, v96, v97
	global_load_dwordx4 v[94:97], v[94:95], off
	s_waitcnt vmcnt(1)
	v_mfma_f32_16x16x32_bf16 v[56:59], v[64:67], v[104:107], v[56:59]
	s_waitcnt vmcnt(0)
	v_mfma_f32_16x16x32_bf16 v[48:51], v[64:67], v[94:97], v[48:51]
	global_load_dwordx4 v[94:97], v[90:91], off offset:-4096
	s_waitcnt vmcnt(0)
	v_mfma_f32_16x16x32_bf16 v[40:43], v[64:67], v[94:97], v[40:43]
	global_load_dwordx4 v[94:97], v[90:91], off
	s_waitcnt vmcnt(0)
	v_mfma_f32_16x16x32_bf16 v[32:35], v[64:67], v[94:97], v[32:35]
	global_load_dwordx4 v[94:97], v[98:99], off offset:-4096
	s_waitcnt vmcnt(0)
	v_mfma_f32_16x16x32_bf16 v[24:27], v[64:67], v[94:97], v[24:27]
	global_load_dwordx4 v[94:97], v[98:99], off
	s_waitcnt vmcnt(0)
	v_mfma_f32_16x16x32_bf16 v[16:19], v[64:67], v[94:97], v[16:19]
	global_load_dwordx4 v[94:97], v[100:101], off offset:-4096
	s_waitcnt vmcnt(0)
	v_mfma_f32_16x16x32_bf16 v[8:11], v[64:67], v[94:97], v[8:11]
	global_load_dwordx4 v[94:97], v[100:101], off
	s_waitcnt vmcnt(0)
	v_mfma_f32_16x16x32_bf16 v[0:3], v[64:67], v[94:97], v[0:3]
	s_add_u32 s36, s36, 64
	s_addc_u32 s37, s37, 0
	s_cmpk_lg_i32 s36, 0x100
	s_cbranch_scc1 .LBB0_1169
	s_ashr_i32 s55, s54, 31
	v_lshlrev_b32_e32 v64, 2, v103
	v_readlane_b32 s60, v255, 10
	s_or_b64 s[4:5], s[54:55], s[0:1]
	v_ashrrev_i32_e32 v65, 31, v64
	v_lshlrev_b32_e32 v92, 1, v102
	v_readlane_b32 s61, v255, 11
	v_readlane_b32 s62, v255, 12
	v_readlane_b32 s63, v255, 13
	v_readlane_b32 s64, v255, 14
	v_readlane_b32 s65, v255, 15
	v_readlane_b32 s66, v255, 16
	v_readlane_b32 s67, v255, 17
	v_readlane_b32 s68, v255, 18
	v_readlane_b32 s69, v255, 19
	v_readlane_b32 s70, v255, 20
	v_readlane_b32 s71, v255, 21
	v_readlane_b32 s72, v255, 22
	v_readlane_b32 s73, v255, 23
	v_readlane_b32 s74, v255, 24
	v_readlane_b32 s75, v255, 25
	v_lshl_add_u64 v[66:67], s[4:5], 0, v[64:65]
	v_lshl_add_u64 v[64:65], s[68:69], 0, v[92:93]
	v_readlane_b32 s60, v254, 38
	v_lshlrev_b32_e32 v72, 2, v102
	v_readlane_b32 s68, v254, 46
	v_readlane_b32 s69, v254, 47
	v_lshlrev_b64 v[74:75], 11, v[66:67]
	v_lshl_add_u64 v[66:67], v[64:65], 0, v[74:75]
	v_readlane_b32 s61, v254, 39
	v_readlane_b32 s62, v254, 40
	v_readlane_b32 s63, v254, 41
	global_load_dword v73, v72, s[68:69] offset:512
	v_readlane_b32 s64, v254, 42
	v_readlane_b32 s65, v254, 43
	v_readlane_b32 s66, v254, 44
	v_readlane_b32 s67, v254, 45
	v_readlane_b32 s70, v254, 48
	v_readlane_b32 s71, v254, 49
	v_readlane_b32 s72, v254, 50
	v_readlane_b32 s73, v254, 51
	v_readlane_b32 s74, v254, 52
	v_readlane_b32 s75, v254, 53
	s_waitcnt vmcnt(0)
	v_mul_f32_e32 v60, v60, v73
	v_cvt_pk_bf16_f32 v60, v60, s0
	global_store_short v[66:67], v60, off offset:256
	v_mul_f32_e32 v60, v61, v73
	v_cvt_pk_bf16_f32 v60, v60, s0
	global_store_short v[66:67], v60, off offset:2304
	v_mul_f32_e32 v60, v62, v73
	v_cvt_pk_bf16_f32 v62, v60, s0
	v_or_b32_e32 v60, 0x1000, v74
	v_mov_b32_e32 v61, v75
	v_lshl_add_u64 v[68:69], v[64:65], 0, v[60:61]
	global_store_short v[68:69], v62, off offset:256
	v_mul_f32_e32 v62, v63, v73
	v_cvt_pk_bf16_f32 v70, v62, s0
	v_or_b32_e32 v62, 0x1800, v74
	v_mov_b32_e32 v63, v75
	v_lshl_add_u64 v[68:69], v[64:65], 0, v[62:63]
	global_store_short v[68:69], v70, off offset:256
	v_mul_f32_e32 v56, v56, v73
	v_add_co_u32_e32 v70, vcc, s91, v66
	v_cvt_pk_bf16_f32 v56, v56, s0
	s_nop 0
	v_addc_co_u32_e32 v71, vcc, 0, v67, vcc
	global_store_short v[70:71], v56, off offset:256
	v_mul_f32_e32 v56, v57, v73
	v_cvt_pk_bf16_f32 v76, v56, s0
	global_store_short v[70:71], v76, off offset:2304
	v_mul_f32_e32 v58, v58, v73
	v_add_co_u32_e32 v76, vcc, s92, v66
	v_cvt_pk_bf16_f32 v58, v58, s0
	s_nop 0
	v_addc_co_u32_e32 v77, vcc, 0, v67, vcc
	global_store_short v[76:77], v58, off offset:256
	v_mul_f32_e32 v58, v59, v73
	v_cvt_pk_bf16_f32 v73, v58, s0
	global_store_short v[76:77], v73, off offset:2304
	global_load_dword v73, v72, s[68:69] offset:576
	v_lshl_add_u64 v[68:69], v[74:75], 0, s[30:31]
	v_lshl_add_u64 v[56:57], v[74:75], 0, s[34:35]
	v_lshl_add_u64 v[70:71], v[74:75], 0, s[38:39]
	v_lshl_add_u64 v[58:59], v[74:75], 0, s[40:41]
	v_lshl_add_u64 v[74:75], v[64:65], 0, 32
	s_waitcnt vmcnt(0)
; template <int W>
; __device__ __forceinline__ void pool_tile(const Params& p, int row0, int g, int wave, int lane_in) {
;     ...
; #pragma unroll
;   for (int n = 0; n < 8; n++) {
;     float cs = p.c_scale[g * 128 + n * 16 + fr];
; #pragma unroll
;     for (int m = 0; m < 2; m++)
; #pragma unroll
;       for (int j = 0; j < 4; j++) {
;         size_t row = (size_t)row0 + wave * 32 + m * 16 + fq * 4 + j;
;         p.mix[row * D + g * 128 + n * 16 + fr] = f2bf(acc[m][n][j] * cs);
;       }
;   }
	v_mul_f32_e32 v52, v52, v73
	v_cvt_pk_bf16_f32 v52, v52, s0
	global_store_short v[66:67], v52, off offset:288
	v_mul_f32_e32 v52, v53, v73
	v_cvt_pk_bf16_f32 v52, v52, s0
	global_store_short v[66:67], v52, off offset:2336
	v_mul_f32_e32 v52, v54, v73
	v_cvt_pk_bf16_f32 v54, v52, s0
	v_lshl_add_u64 v[52:53], v[74:75], 0, v[60:61]
	global_store_short v[52:53], v54, off offset:256
	v_mul_f32_e32 v52, v55, v73
	v_cvt_pk_bf16_f32 v54, v52, s0
	v_lshl_add_u64 v[52:53], v[74:75], 0, v[62:63]
	v_mul_f32_e32 v48, v48, v73
	global_store_short v[52:53], v54, off offset:256
	v_cvt_pk_bf16_f32 v48, v48, s0
	v_lshl_add_u64 v[52:53], v[74:75], 0, v[68:69]
	global_store_short v[52:53], v48, off offset:256
	v_mul_f32_e32 v48, v49, v73
	v_cvt_pk_bf16_f32 v52, v48, s0
	v_lshl_add_u64 v[48:49], v[74:75], 0, v[56:57]
	global_store_short v[48:49], v52, off offset:256
	v_mul_f32_e32 v48, v50, v73
	v_cvt_pk_bf16_f32 v50, v48, s0
	v_lshl_add_u64 v[48:49], v[74:75], 0, v[70:71]
	global_store_short v[48:49], v50, off offset:256
	v_mul_f32_e32 v48, v51, v73
	v_cvt_pk_bf16_f32 v50, v48, s0
	v_lshl_add_u64 v[48:49], v[74:75], 0, v[58:59]
	global_store_short v[48:49], v50, off offset:256
	global_load_dword v50, v72, s[68:69] offset:640
	v_lshl_add_u64 v[48:49], v[64:65], 0, 64
	s_waitcnt vmcnt(0)
	v_mul_f32_e32 v44, v44, v50
	v_cvt_pk_bf16_f32 v44, v44, s0
	global_store_short v[66:67], v44, off offset:320
	v_mul_f32_e32 v44, v45, v50
	v_cvt_pk_bf16_f32 v44, v44, s0
	global_store_short v[66:67], v44, off offset:2368
	v_mul_f32_e32 v44, v46, v50
	v_cvt_pk_bf16_f32 v46, v44, s0
	v_lshl_add_u64 v[44:45], v[48:49], 0, v[60:61]
	global_store_short v[44:45], v46, off offset:256
	v_mul_f32_e32 v44, v47, v50
	v_cvt_pk_bf16_f32 v46, v44, s0
	v_lshl_add_u64 v[44:45], v[48:49], 0, v[62:63]
	v_mul_f32_e32 v40, v40, v50
	global_store_short v[44:45], v46, off offset:256
	v_cvt_pk_bf16_f32 v40, v40, s0
	v_lshl_add_u64 v[44:45], v[48:49], 0, v[68:69]
	global_store_short v[44:45], v40, off offset:256
	v_mul_f32_e32 v40, v41, v50
	v_cvt_pk_bf16_f32 v44, v40, s0
	v_lshl_add_u64 v[40:41], v[48:49], 0, v[56:57]
	global_store_short v[40:41], v44, off offset:256
	v_mul_f32_e32 v40, v42, v50
	v_cvt_pk_bf16_f32 v42, v40, s0
	v_lshl_add_u64 v[40:41], v[48:49], 0, v[70:71]
	global_store_short v[40:41], v42, off offset:256
	v_mul_f32_e32 v40, v43, v50
	v_cvt_pk_bf16_f32 v42, v40, s0
	v_lshl_add_u64 v[40:41], v[48:49], 0, v[58:59]
	global_store_short v[40:41], v42, off offset:256
	global_load_dword v42, v72, s[68:69] offset:704
	v_lshl_add_u64 v[40:41], v[64:65], 0, s[42:43]
	s_waitcnt vmcnt(0)
	v_mul_f32_e32 v36, v36, v42
	v_cvt_pk_bf16_f32 v36, v36, s0
	global_store_short v[66:67], v36, off offset:352
	v_mul_f32_e32 v36, v37, v42
	v_cvt_pk_bf16_f32 v36, v36, s0
	global_store_short v[66:67], v36, off offset:2400
	v_mul_f32_e32 v36, v38, v42
	v_cvt_pk_bf16_f32 v38, v36, s0
	v_lshl_add_u64 v[36:37], v[40:41], 0, v[60:61]
	global_store_short v[36:37], v38, off offset:256
	v_mul_f32_e32 v36, v39, v42
	v_cvt_pk_bf16_f32 v38, v36, s0
	v_lshl_add_u64 v[36:37], v[40:41], 0, v[62:63]
	v_mul_f32_e32 v32, v32, v42
	global_store_short v[36:37], v38, off offset:256
	v_cvt_pk_bf16_f32 v32, v32, s0
	v_lshl_add_u64 v[36:37], v[40:41], 0, v[68:69]
	global_store_short v[36:37], v32, off offset:256
	v_mul_f32_e32 v32, v33, v42
	v_cvt_pk_bf16_f32 v36, v32, s0
	v_lshl_add_u64 v[32:33], v[40:41], 0, v[56:57]
	global_store_short v[32:33], v36, off offset:256
	v_mul_f32_e32 v32, v34, v42
	v_cvt_pk_bf16_f32 v34, v32, s0
	v_lshl_add_u64 v[32:33], v[40:41], 0, v[70:71]
	global_store_short v[32:33], v34, off offset:256
	v_mul_f32_e32 v32, v35, v42
	v_cvt_pk_bf16_f32 v34, v32, s0
	v_lshl_add_u64 v[32:33], v[40:41], 0, v[58:59]
	global_store_short v[32:33], v34, off offset:256
	global_load_dword v34, v72, s[68:69] offset:768
	v_lshl_add_u64 v[32:33], v[64:65], 0, s[44:45]
	s_waitcnt vmcnt(0)
; template <int W>
; __device__ __forceinline__ void pool_tile(const Params& p, int row0, int g, int wave, int lane_in) {
;     ...
; #pragma unroll
;   for (int n = 0; n < 8; n++) {
;     float cs = p.c_scale[g * 128 + n * 16 + fr];
; #pragma unroll
;     for (int m = 0; m < 2; m++)
; #pragma unroll
;       for (int j = 0; j < 4; j++) {
;         size_t row = (size_t)row0 + wave * 32 + m * 16 + fq * 4 + j;
;         p.mix[row * D + g * 128 + n * 16 + fr] = f2bf(acc[m][n][j] * cs);
;       }
;   }
; __device__ __forceinline__ void mixC_phase(const Params& p) {
;     ...
;   for (int task = blockIdx.x * 2 + (wave8 >> 2); task < ntask; task += gridDim.x * 2) {
;     int g = (task + (task >> 9)) & 3, row0 = (task >> 2) * 128;
;     if (g == 0) pool_tile<2>(p, row0, 0, wave, lane);
;     else if (g == 1) pool_tile<4>(p, row0, 1, wave, lane);
;     else if (g == 2) pool_tile<8>(p, row0, 2, wave, lane);
;     else pool_tile<16>(p, row0, 3, wave, lane);
;   }
	v_mul_f32_e32 v28, v28, v34
	v_cvt_pk_bf16_f32 v28, v28, s0
	global_store_short v[66:67], v28, off offset:384
	v_mul_f32_e32 v28, v29, v34
	v_cvt_pk_bf16_f32 v28, v28, s0
	global_store_short v[66:67], v28, off offset:2432
	v_mul_f32_e32 v28, v30, v34
	v_cvt_pk_bf16_f32 v30, v28, s0
	v_lshl_add_u64 v[28:29], v[32:33], 0, v[60:61]
	global_store_short v[28:29], v30, off offset:256
	v_mul_f32_e32 v28, v31, v34
	v_cvt_pk_bf16_f32 v30, v28, s0
	v_lshl_add_u64 v[28:29], v[32:33], 0, v[62:63]
	v_mul_f32_e32 v24, v24, v34
	global_store_short v[28:29], v30, off offset:256
	v_cvt_pk_bf16_f32 v24, v24, s0
	v_lshl_add_u64 v[28:29], v[32:33], 0, v[68:69]
	global_store_short v[28:29], v24, off offset:256
	v_mul_f32_e32 v24, v25, v34
	v_cvt_pk_bf16_f32 v28, v24, s0
	v_lshl_add_u64 v[24:25], v[32:33], 0, v[56:57]
	global_store_short v[24:25], v28, off offset:256
	v_mul_f32_e32 v24, v26, v34
	v_cvt_pk_bf16_f32 v26, v24, s0
	v_lshl_add_u64 v[24:25], v[32:33], 0, v[70:71]
	global_store_short v[24:25], v26, off offset:256
	v_mul_f32_e32 v24, v27, v34
	v_cvt_pk_bf16_f32 v26, v24, s0
	v_lshl_add_u64 v[24:25], v[32:33], 0, v[58:59]
	global_store_short v[24:25], v26, off offset:256
	global_load_dword v26, v72, s[68:69] offset:832
	v_lshl_add_u64 v[24:25], v[64:65], 0, s[46:47]
	s_waitcnt vmcnt(0)
	v_mul_f32_e32 v20, v20, v26
	v_cvt_pk_bf16_f32 v20, v20, s0
	global_store_short v[66:67], v20, off offset:416
	v_mul_f32_e32 v20, v21, v26
	v_cvt_pk_bf16_f32 v20, v20, s0
	global_store_short v[66:67], v20, off offset:2464
	v_mul_f32_e32 v20, v22, v26
	v_cvt_pk_bf16_f32 v22, v20, s0
	v_lshl_add_u64 v[20:21], v[24:25], 0, v[60:61]
	global_store_short v[20:21], v22, off offset:256
	v_mul_f32_e32 v20, v23, v26
	v_cvt_pk_bf16_f32 v22, v20, s0
	v_lshl_add_u64 v[20:21], v[24:25], 0, v[62:63]
	v_mul_f32_e32 v16, v16, v26
	global_store_short v[20:21], v22, off offset:256
	v_cvt_pk_bf16_f32 v16, v16, s0
	v_lshl_add_u64 v[20:21], v[24:25], 0, v[68:69]
	global_store_short v[20:21], v16, off offset:256
	v_mul_f32_e32 v16, v17, v26
	v_cvt_pk_bf16_f32 v20, v16, s0
	v_lshl_add_u64 v[16:17], v[24:25], 0, v[56:57]
	global_store_short v[16:17], v20, off offset:256
	v_mul_f32_e32 v16, v18, v26
	v_cvt_pk_bf16_f32 v18, v16, s0
	v_lshl_add_u64 v[16:17], v[24:25], 0, v[70:71]
	global_store_short v[16:17], v18, off offset:256
	v_mul_f32_e32 v16, v19, v26
	v_cvt_pk_bf16_f32 v18, v16, s0
	v_lshl_add_u64 v[16:17], v[24:25], 0, v[58:59]
	global_store_short v[16:17], v18, off offset:256
	global_load_dword v18, v72, s[68:69] offset:896
	v_lshl_add_u64 v[16:17], v[64:65], 0, s[48:49]
	s_waitcnt vmcnt(0)
	v_mul_f32_e32 v12, v12, v18
	v_cvt_pk_bf16_f32 v12, v12, s0
	global_store_short v[66:67], v12, off offset:448
	v_mul_f32_e32 v12, v13, v18
	v_cvt_pk_bf16_f32 v12, v12, s0
	global_store_short v[66:67], v12, off offset:2496
	v_mul_f32_e32 v12, v14, v18
	v_cvt_pk_bf16_f32 v14, v12, s0
	v_lshl_add_u64 v[12:13], v[16:17], 0, v[60:61]
	global_store_short v[12:13], v14, off offset:256
	v_mul_f32_e32 v12, v15, v18
	v_cvt_pk_bf16_f32 v14, v12, s0
	v_lshl_add_u64 v[12:13], v[16:17], 0, v[62:63]
	v_mul_f32_e32 v8, v8, v18
	global_store_short v[12:13], v14, off offset:256
	v_cvt_pk_bf16_f32 v8, v8, s0
	v_lshl_add_u64 v[12:13], v[16:17], 0, v[68:69]
	global_store_short v[12:13], v8, off offset:256
	v_mul_f32_e32 v8, v9, v18
	v_cvt_pk_bf16_f32 v12, v8, s0
	v_lshl_add_u64 v[8:9], v[16:17], 0, v[56:57]
	global_store_short v[8:9], v12, off offset:256
	v_mul_f32_e32 v8, v10, v18
	v_cvt_pk_bf16_f32 v10, v8, s0
	v_lshl_add_u64 v[8:9], v[16:17], 0, v[70:71]
	global_store_short v[8:9], v10, off offset:256
	v_mul_f32_e32 v8, v11, v18
	v_cvt_pk_bf16_f32 v10, v8, s0
	v_lshl_add_u64 v[8:9], v[16:17], 0, v[58:59]
	global_store_short v[8:9], v10, off offset:256
	global_load_dword v8, v72, s[68:69] offset:960
	v_lshl_add_u64 v[10:11], v[64:65], 0, s[50:51]
	s_waitcnt vmcnt(0)
	v_mul_f32_e32 v4, v4, v8
	v_cvt_pk_bf16_f32 v4, v4, s0
	global_store_short v[66:67], v4, off offset:480
	v_mul_f32_e32 v4, v5, v8
	v_cvt_pk_bf16_f32 v4, v4, s0
	global_store_short v[66:67], v4, off offset:2528
	v_mul_f32_e32 v4, v6, v8
	v_cvt_pk_bf16_f32 v6, v4, s0
	v_lshl_add_u64 v[4:5], v[10:11], 0, v[60:61]
	global_store_short v[4:5], v6, off offset:256
	v_mul_f32_e32 v4, v7, v8
	v_cvt_pk_bf16_f32 v6, v4, s0
	v_lshl_add_u64 v[4:5], v[10:11], 0, v[62:63]
	v_mul_f32_e32 v0, v0, v8
	global_store_short v[4:5], v6, off offset:256
	v_cvt_pk_bf16_f32 v0, v0, s0
	v_lshl_add_u64 v[4:5], v[10:11], 0, v[68:69]
	global_store_short v[4:5], v0, off offset:256
	v_mul_f32_e32 v0, v1, v8
	v_cvt_pk_bf16_f32 v4, v0, s0
	v_lshl_add_u64 v[0:1], v[10:11], 0, v[56:57]
	global_store_short v[0:1], v4, off offset:256
	v_mul_f32_e32 v0, v2, v8
	v_cvt_pk_bf16_f32 v2, v0, s0
	v_lshl_add_u64 v[0:1], v[10:11], 0, v[70:71]
	global_store_short v[0:1], v2, off offset:256
	v_mul_f32_e32 v0, v3, v8
	v_cvt_pk_bf16_f32 v2, v0, s0
	v_lshl_add_u64 v[0:1], v[10:11], 0, v[58:59]
	global_store_short v[0:1], v2, off offset:256
	s_branch .LBB0_1151
